# mid-block s_setprio 0/3 toggles removed from the second wave half's MFMA blocks in all five K-loops
# speedup vs baseline: 1.0043x; 1.0000x over previous
; #define PG8_STAGE(bufoff, gbase, voff) do { _Pragma("unroll") for (int _i = 0; _i < 2; ++_i) \
;         __builtin_amdgcn_global_load_lds((const unsigned*)((const char*)(gbase) + (voff)[_i]), (PG8_LAS unsigned*)(lds + (bufoff) + ldsw + _i * 8192), 16, 0, 0); } while (0)
; #define PG8_LDA(dst, b, h) do { _Pragma("unroll") for (int m = 0; m < 4; ++m) _Pragma("unroll") for (int k = 0; k < 2; ++k) dst[m][k] = *(const PG8_LAS bf16x8*)(lds + PG8_SA(b, h) + aoff + m * 2048 + k * 1024); } while (0)
; #define PG8_LDB(dst, b, h) do { _Pragma("unroll") for (int n = 0; n < 2; ++n) _Pragma("unroll") for (int k = 0; k < 2; ++k) dst[n][k] = *(const PG8_LAS bf16x8*)(lds + PG8_SB(b, h) + boff + n * 2048 + k * 1024); } while (0)
; #define PG8_WAIT_V(n) asm volatile("s_waitcnt vmcnt(" #n ")" ::: "memory")
; #define PG8_WAIT_L(n) asm volatile("s_waitcnt lgkmcnt(" #n ")" ::: "memory")
; #define PG8_BAR __builtin_amdgcn_s_barrier()
; #define PG8_SCHED __builtin_amdgcn_sched_barrier(0)
; template <class Epi, class Sched, bool ALIGN_EPI = false, bool SP2 = false, bool F8 = false>
; __device__ __forceinline__ void gemm_phase(PG8_LAS unsigned char* lds, const Gemm g, const Sched& S, const Epi& E) {
;     ...
;             PG8_LDB(B0, 0, 0); PG8_LDB(B1, 0, 1); PG8_SCHED; PG8_LDA(At, 0, 0); PG8_STAGE(PG8_SA(1, 1), a1 + hstepA, voffA);
;             PG8_WAIT_V(8); PG8_WAIT_L(0); PG8_BAR; PG8_MMA(0, 0, At, B0); PG8_MMA(0, 1, At, B1); PG8_BAR; PG8_SCHED;
.Lk0_Y:
	ds_read_b128 v[130:133], v225
	ds_read_b128 v[134:137], v225 offset:1024
	ds_read_b128 v[138:141], v225 offset:2048
	ds_read_b128 v[142:145], v225 offset:3072
	ds_read_b128 v[146:149], v226
	ds_read_b128 v[150:153], v226 offset:1024
	ds_read_b128 v[154:157], v226 offset:2048
	ds_read_b128 v[158:161], v226 offset:3072
	s_add_u32 s24, s84, 0xfff80080
	s_addc_u32 s25, s85, -1
	s_cmp_eq_u32 s54, 28
	s_cselect_b32 s89, s13, s25
	s_cselect_b32 s88, s53, s24
	s_cselect_b32 s87, s77, vcc_hi
	s_cselect_b32 s86, s79, vcc_lo
	s_add_i32 m0, s95, 0xc000
	ds_read_b128 v[192:195], v227
	ds_read_b128 v[196:199], v227 offset:1024
	ds_read_b128 v[200:203], v227 offset:2048
	ds_read_b128 v[204:207], v227 offset:3072
	ds_read_b128 v[230:233], v227 offset:4096
	ds_read_b128 v[234:237], v227 offset:5120
	ds_read_b128 v[238:241], v227 offset:6144
	ds_read_b128 v[242:245], v227 offset:7168
	global_load_lds_dwordx4 v186, s[84:85]
	s_add_i32 m0, s95, 0xe000
	s_nop 0
	global_load_lds_dwordx4 v188, s[84:85]
	s_waitcnt vmcnt(8)
	s_waitcnt lgkmcnt(0)
	s_barrier
	s_setprio 3
	s_waitcnt lgkmcnt(0)
	v_mfma_f32_16x16x32_bf16 v[126:129], v[130:133], v[192:195], v[126:129]
	v_mfma_f32_16x16x32_bf16 v[122:125], v[138:141], v[192:195], v[122:125]
	v_mfma_f32_16x16x32_bf16 v[110:113], v[130:133], v[200:203], v[110:113]
	v_mfma_f32_16x16x32_bf16 v[106:109], v[138:141], v[200:203], v[106:109]
	v_mfma_f32_16x16x32_bf16 v[94:97], v[130:133], v[230:233], v[94:97]
	v_mfma_f32_16x16x32_bf16 v[90:93], v[138:141], v[230:233], v[90:93]
	v_mfma_f32_16x16x32_bf16 v[78:81], v[130:133], v[238:241], v[78:81]
	v_mfma_f32_16x16x32_bf16 v[74:77], v[138:141], v[238:241], v[74:77]
	v_mfma_f32_16x16x32_bf16 v[126:129], v[134:137], v[196:199], v[126:129]
	v_mfma_f32_16x16x32_bf16 v[122:125], v[142:145], v[196:199], v[122:125]
	v_mfma_f32_16x16x32_bf16 v[110:113], v[134:137], v[204:207], v[110:113]
	v_mfma_f32_16x16x32_bf16 v[106:109], v[142:145], v[204:207], v[106:109]
	v_mfma_f32_16x16x32_bf16 v[94:97], v[134:137], v[234:237], v[94:97]
	v_mfma_f32_16x16x32_bf16 v[90:93], v[142:145], v[234:237], v[90:93]
	v_mfma_f32_16x16x32_bf16 v[78:81], v[134:137], v[242:245], v[78:81]
	v_mfma_f32_16x16x32_bf16 v[74:77], v[142:145], v[242:245], v[74:77]


; #define PG8_STAGE(bufoff, gbase, voff) do { _Pragma("unroll") for (int _i = 0; _i < 2; ++_i) \
;         __builtin_amdgcn_global_load_lds((const unsigned*)((const char*)(gbase) + (voff)[_i]), (PG8_LAS unsigned*)(lds + (bufoff) + ldsw + _i * 8192), 16, 0, 0); } while (0)
; #define PG8_LDA(dst, b, h) do { _Pragma("unroll") for (int m = 0; m < 4; ++m) _Pragma("unroll") for (int k = 0; k < 2; ++k) dst[m][k] = *(const PG8_LAS bf16x8*)(lds + PG8_SA(b, h) + aoff + m * 2048 + k * 1024); } while (0)
; #define PG8_WAIT_V(n) asm volatile("s_waitcnt vmcnt(" #n ")" ::: "memory")
; #define PG8_WAIT_L(n) asm volatile("s_waitcnt lgkmcnt(" #n ")" ::: "memory")
; #define PG8_BAR __builtin_amdgcn_s_barrier()
; #define PG8_SCHED __builtin_amdgcn_sched_barrier(0)
; template <class Epi, class Sched, bool ALIGN_EPI = false, bool SP2 = false, bool F8 = false>
; __device__ __forceinline__ void gemm_phase(PG8_LAS unsigned char* lds, const Gemm g, const Sched& S, const Epi& E) {
;     ...
;             PG8_WAIT_V(8); PG8_WAIT_L(0); PG8_BAR; PG8_MMA(0, 0, At, B0); PG8_MMA(0, 1, At, B1); PG8_BAR; PG8_SCHED;
;             PG8_LDA(At, 0, 1); PG8_STAGE(PG8_SB(0, 0), b2, voffB); PG8_STAGE(PG8_SB(0, 1), b2 + hstep, voffB); PG8_STAGE(PG8_SA(0, 0), a2, voffA);
;             PG8_WAIT_V(8); PG8_WAIT_L(0); PG8_BAR; PG8_MMA(1, 0, At, B0); PG8_MMA(1, 1, At, B1); PG8_BAR; PG8_SCHED;
	v_mfma_f32_16x16x32_bf16 v[118:121], v[146:149], v[192:195], v[118:121]
	v_mfma_f32_16x16x32_bf16 v[114:117], v[154:157], v[192:195], v[114:117]
	v_mfma_f32_16x16x32_bf16 v[102:105], v[146:149], v[200:203], v[102:105]
	v_mfma_f32_16x16x32_bf16 v[98:101], v[154:157], v[200:203], v[98:101]
	v_mfma_f32_16x16x32_bf16 v[86:89], v[146:149], v[230:233], v[86:89]
	v_mfma_f32_16x16x32_bf16 v[82:85], v[154:157], v[230:233], v[82:85]
	v_mfma_f32_16x16x32_bf16 v[70:73], v[146:149], v[238:241], v[70:73]
	v_mfma_f32_16x16x32_bf16 v[66:69], v[154:157], v[238:241], v[66:69]
	v_mfma_f32_16x16x32_bf16 v[118:121], v[150:153], v[196:199], v[118:121]
	v_mfma_f32_16x16x32_bf16 v[114:117], v[158:161], v[196:199], v[114:117]
	v_mfma_f32_16x16x32_bf16 v[102:105], v[150:153], v[204:207], v[102:105]
	v_mfma_f32_16x16x32_bf16 v[98:101], v[158:161], v[204:207], v[98:101]
	v_mfma_f32_16x16x32_bf16 v[86:89], v[150:153], v[234:237], v[86:89]
	v_mfma_f32_16x16x32_bf16 v[82:85], v[158:161], v[234:237], v[82:85]
	v_mfma_f32_16x16x32_bf16 v[70:73], v[150:153], v[242:245], v[70:73]
	v_mfma_f32_16x16x32_bf16 v[66:69], v[158:161], v[242:245], v[66:69]
	s_setprio 0
	s_add_i32 s24, s45, s23
	s_mov_b32 m0, s24
	ds_read_b128 v[192:195], v227 offset:16384
	ds_read_b128 v[196:199], v227 offset:17408
	ds_read_b128 v[200:203], v227 offset:18432
	ds_read_b128 v[204:207], v227 offset:19456
	ds_read_b128 v[230:233], v227 offset:20480
	ds_read_b128 v[234:237], v227 offset:21504
	ds_read_b128 v[238:241], v227 offset:22528
	ds_read_b128 v[242:245], v227 offset:23552
	global_load_lds_dwordx4 v168, s[86:87]
	s_add_i32 m0, s24, 0x2000
	s_add_u32 s24, s86, 0x80000
	s_addc_u32 s25, s87, 0
	s_add_i32 s55, s33, s23
	global_load_lds_dwordx4 v164, s[86:87]
	s_mov_b32 m0, s55
	s_nop 0
	global_load_lds_dwordx4 v168, s[24:25]
	s_add_i32 m0, s55, 0x2000
	s_nop 0
	global_load_lds_dwordx4 v164, s[24:25]
	s_mov_b32 m0, s95
	s_nop 0
	global_load_lds_dwordx4 v170, s[88:89]
	s_mov_b32 m0, s96
	s_nop 0
	global_load_lds_dwordx4 v166, s[88:89]
	s_waitcnt vmcnt(8)
	s_waitcnt lgkmcnt(0)
	s_barrier
	s_setprio 3
	s_waitcnt lgkmcnt(0)
	v_mfma_f32_16x16x32_bf16 v[62:65], v[130:133], v[192:195], v[62:65]
	v_mfma_f32_16x16x32_bf16 v[58:61], v[138:141], v[192:195], v[58:61]
	v_mfma_f32_16x16x32_bf16 v[46:49], v[130:133], v[200:203], v[46:49]
	v_mfma_f32_16x16x32_bf16 v[42:45], v[138:141], v[200:203], v[42:45]
	v_mfma_f32_16x16x32_bf16 v[30:33], v[130:133], v[230:233], v[30:33]
	v_mfma_f32_16x16x32_bf16 v[26:29], v[138:141], v[230:233], v[26:29]
	v_mfma_f32_16x16x32_bf16 v[14:17], v[130:133], v[238:241], v[14:17]
	v_mfma_f32_16x16x32_bf16 v[10:13], v[138:141], v[238:241], v[10:13]
	v_mfma_f32_16x16x32_bf16 v[62:65], v[134:137], v[196:199], v[62:65]
	v_mfma_f32_16x16x32_bf16 v[58:61], v[142:145], v[196:199], v[58:61]
	v_mfma_f32_16x16x32_bf16 v[46:49], v[134:137], v[204:207], v[46:49]
	v_mfma_f32_16x16x32_bf16 v[42:45], v[142:145], v[204:207], v[42:45]
	v_mfma_f32_16x16x32_bf16 v[30:33], v[134:137], v[234:237], v[30:33]
	v_mfma_f32_16x16x32_bf16 v[26:29], v[142:145], v[234:237], v[26:29]
	v_mfma_f32_16x16x32_bf16 v[14:17], v[134:137], v[242:245], v[14:17]
	v_mfma_f32_16x16x32_bf16 v[10:13], v[142:145], v[242:245], v[10:13]


; #define PG8_STAGE(bufoff, gbase, voff) do { _Pragma("unroll") for (int _i = 0; _i < 2; ++_i) \
;         __builtin_amdgcn_global_load_lds((const unsigned*)((const char*)(gbase) + (voff)[_i]), (PG8_LAS unsigned*)(lds + (bufoff) + ldsw + _i * 8192), 16, 0, 0); } while (0)
; #define PG8_LDA(dst, b, h) do { _Pragma("unroll") for (int m = 0; m < 4; ++m) _Pragma("unroll") for (int k = 0; k < 2; ++k) dst[m][k] = *(const PG8_LAS bf16x8*)(lds + PG8_SA(b, h) + aoff + m * 2048 + k * 1024); } while (0)
; #define PG8_LDB(dst, b, h) do { _Pragma("unroll") for (int n = 0; n < 2; ++n) _Pragma("unroll") for (int k = 0; k < 2; ++k) dst[n][k] = *(const PG8_LAS bf16x8*)(lds + PG8_SB(b, h) + boff + n * 2048 + k * 1024); } while (0)
; #define PG8_WAIT_V(n) asm volatile("s_waitcnt vmcnt(" #n ")" ::: "memory")
; #define PG8_WAIT_L(n) asm volatile("s_waitcnt lgkmcnt(" #n ")" ::: "memory")
; #define PG8_BAR __builtin_amdgcn_s_barrier()
; #define PG8_SCHED __builtin_amdgcn_sched_barrier(0)
; template <class Epi, class Sched, bool ALIGN_EPI = false, bool SP2 = false, bool F8 = false>
; __device__ __forceinline__ void gemm_phase(PG8_LAS unsigned char* lds, const Gemm g, const Sched& S, const Epi& E) {
;     ...
;             PG8_WAIT_V(8); PG8_WAIT_L(0); PG8_BAR; PG8_MMA(1, 0, At, B0); PG8_MMA(1, 1, At, B1); PG8_BAR; PG8_SCHED;
;             PG8_LDB(B0, 1, 0); PG8_LDB(B1, 1, 1); PG8_SCHED; PG8_LDA(At, 1, 0); PG8_STAGE(PG8_SA(0, 1), a2 + hstepA, voffA);
;             PG8_WAIT_V(8); PG8_WAIT_L(0); PG8_BAR; PG8_MMA(0, 0, At, B0); PG8_MMA(0, 1, At, B1); PG8_BAR; PG8_SCHED;
	v_mfma_f32_16x16x32_bf16 v[54:57], v[146:149], v[192:195], v[54:57]
	v_mfma_f32_16x16x32_bf16 v[50:53], v[154:157], v[192:195], v[50:53]
	v_mfma_f32_16x16x32_bf16 v[38:41], v[146:149], v[200:203], v[38:41]
	v_mfma_f32_16x16x32_bf16 v[34:37], v[154:157], v[200:203], v[34:37]
	v_mfma_f32_16x16x32_bf16 v[22:25], v[146:149], v[230:233], v[22:25]
	v_mfma_f32_16x16x32_bf16 v[18:21], v[154:157], v[230:233], v[18:21]
	v_mfma_f32_16x16x32_bf16 v[6:9], v[146:149], v[238:241], v[6:9]
	v_mfma_f32_16x16x32_bf16 v[2:5], v[154:157], v[238:241], v[2:5]
	v_mfma_f32_16x16x32_bf16 v[54:57], v[150:153], v[196:199], v[54:57]
	v_mfma_f32_16x16x32_bf16 v[50:53], v[158:161], v[196:199], v[50:53]
	v_mfma_f32_16x16x32_bf16 v[38:41], v[150:153], v[204:207], v[38:41]
	v_mfma_f32_16x16x32_bf16 v[34:37], v[158:161], v[204:207], v[34:37]
	v_mfma_f32_16x16x32_bf16 v[22:25], v[150:153], v[234:237], v[22:25]
	v_mfma_f32_16x16x32_bf16 v[18:21], v[158:161], v[234:237], v[18:21]
	v_mfma_f32_16x16x32_bf16 v[6:9], v[150:153], v[242:245], v[6:9]
	v_mfma_f32_16x16x32_bf16 v[2:5], v[158:161], v[242:245], v[2:5]
	s_setprio 0
	s_add_i32 s55, 0, 0x18000
	s_add_i32 s36, 0, 0x1c000
	v_add_u32_e32 v142, s55, v222
	v_add_u32_e32 v158, s36, v222
	ds_read_b128 v[130:133], v142
	ds_read_b128 v[134:137], v142 offset:1024
	ds_read_b128 v[138:141], v142 offset:2048
	ds_read_b128 v[142:145], v142 offset:3072
	ds_read_b128 v[146:149], v158
	ds_read_b128 v[150:153], v158 offset:1024
	ds_read_b128 v[154:157], v158 offset:2048
	ds_read_b128 v[158:161], v158 offset:3072
	s_add_u32 s24, s88, 0x80000
	s_addc_u32 s25, s89, 0
	s_mov_b32 m0, s97
	ds_read_b128 v[192:195], v227 offset:32768
	ds_read_b128 v[196:199], v227 offset:33792
	ds_read_b128 v[200:203], v227 offset:34816
	ds_read_b128 v[204:207], v227 offset:35840
	ds_read_b128 v[230:233], v227 offset:36864
	ds_read_b128 v[234:237], v227 offset:37888
	ds_read_b128 v[238:241], v227 offset:38912
	ds_read_b128 v[242:245], v227 offset:39936
	global_load_lds_dwordx4 v170, s[24:25]
	s_mov_b32 m0, s28
	s_nop 0
	global_load_lds_dwordx4 v166, s[24:25]
	s_waitcnt vmcnt(8)
	s_waitcnt lgkmcnt(0)
	s_barrier
	s_setprio 3
	s_waitcnt lgkmcnt(0)
	v_mfma_f32_16x16x32_bf16 v[126:129], v[130:133], v[192:195], v[126:129]
	v_mfma_f32_16x16x32_bf16 v[122:125], v[138:141], v[192:195], v[122:125]
	v_mfma_f32_16x16x32_bf16 v[110:113], v[130:133], v[200:203], v[110:113]
	v_mfma_f32_16x16x32_bf16 v[106:109], v[138:141], v[200:203], v[106:109]
	v_mfma_f32_16x16x32_bf16 v[94:97], v[130:133], v[230:233], v[94:97]
	v_mfma_f32_16x16x32_bf16 v[90:93], v[138:141], v[230:233], v[90:93]
	v_mfma_f32_16x16x32_bf16 v[78:81], v[130:133], v[238:241], v[78:81]
	v_mfma_f32_16x16x32_bf16 v[74:77], v[138:141], v[238:241], v[74:77]
	v_mfma_f32_16x16x32_bf16 v[126:129], v[134:137], v[196:199], v[126:129]
	v_mfma_f32_16x16x32_bf16 v[122:125], v[142:145], v[196:199], v[122:125]
	v_mfma_f32_16x16x32_bf16 v[110:113], v[134:137], v[204:207], v[110:113]
	v_mfma_f32_16x16x32_bf16 v[106:109], v[142:145], v[204:207], v[106:109]
	v_mfma_f32_16x16x32_bf16 v[94:97], v[134:137], v[234:237], v[94:97]
	v_mfma_f32_16x16x32_bf16 v[90:93], v[142:145], v[234:237], v[90:93]
	v_mfma_f32_16x16x32_bf16 v[78:81], v[134:137], v[242:245], v[78:81]
	v_mfma_f32_16x16x32_bf16 v[74:77], v[142:145], v[242:245], v[74:77]


; #define PG8_STAGE(bufoff, gbase, voff) do { _Pragma("unroll") for (int _i = 0; _i < 2; ++_i) \
;         __builtin_amdgcn_global_load_lds((const unsigned*)((const char*)(gbase) + (voff)[_i]), (PG8_LAS unsigned*)(lds + (bufoff) + ldsw + _i * 8192), 16, 0, 0); } while (0)
; #define PG8_LDA(dst, b, h) do { _Pragma("unroll") for (int m = 0; m < 4; ++m) _Pragma("unroll") for (int k = 0; k < 2; ++k) dst[m][k] = *(const PG8_LAS bf16x8*)(lds + PG8_SA(b, h) + aoff + m * 2048 + k * 1024); } while (0)
; #define PG8_WAIT_V(n) asm volatile("s_waitcnt vmcnt(" #n ")" ::: "memory")
; #define PG8_WAIT_L(n) asm volatile("s_waitcnt lgkmcnt(" #n ")" ::: "memory")
; #define PG8_BAR __builtin_amdgcn_s_barrier()
; #define PG8_SCHED __builtin_amdgcn_sched_barrier(0)
; template <class Epi, class Sched, bool ALIGN_EPI = false, bool SP2 = false, bool F8 = false>
; __device__ __forceinline__ void gemm_phase(PG8_LAS unsigned char* lds, const Gemm g, const Sched& S, const Epi& E) {
;     ...
;             PG8_WAIT_V(8); PG8_WAIT_L(0); PG8_BAR; PG8_MMA(0, 0, At, B0); PG8_MMA(0, 1, At, B1); PG8_BAR; PG8_SCHED;
;             PG8_LDA(At, 1, 1); PG8_STAGE(PG8_SB(1, 0), b3, voffB); PG8_STAGE(PG8_SB(1, 1), b3 + hstep, voffB); PG8_STAGE(PG8_SA(1, 0), a3, voffA);
;             PG8_WAIT_V(8); PG8_WAIT_L(0); PG8_BAR; PG8_MMA(1, 0, At, B0); PG8_MMA(1, 1, At, B1); PG8_BAR; PG8_SCHED;
	v_mfma_f32_16x16x32_bf16 v[118:121], v[146:149], v[192:195], v[118:121]
	v_mfma_f32_16x16x32_bf16 v[114:117], v[154:157], v[192:195], v[114:117]
	v_mfma_f32_16x16x32_bf16 v[102:105], v[146:149], v[200:203], v[102:105]
	v_mfma_f32_16x16x32_bf16 v[98:101], v[154:157], v[200:203], v[98:101]
	v_mfma_f32_16x16x32_bf16 v[86:89], v[146:149], v[230:233], v[86:89]
	v_mfma_f32_16x16x32_bf16 v[82:85], v[154:157], v[230:233], v[82:85]
	v_mfma_f32_16x16x32_bf16 v[70:73], v[146:149], v[238:241], v[70:73]
	v_mfma_f32_16x16x32_bf16 v[66:69], v[154:157], v[238:241], v[66:69]
	v_mfma_f32_16x16x32_bf16 v[118:121], v[150:153], v[196:199], v[118:121]
	v_mfma_f32_16x16x32_bf16 v[114:117], v[158:161], v[196:199], v[114:117]
	v_mfma_f32_16x16x32_bf16 v[102:105], v[150:153], v[204:207], v[102:105]
	v_mfma_f32_16x16x32_bf16 v[98:101], v[158:161], v[204:207], v[98:101]
	v_mfma_f32_16x16x32_bf16 v[86:89], v[150:153], v[234:237], v[86:89]
	v_mfma_f32_16x16x32_bf16 v[82:85], v[158:161], v[234:237], v[82:85]
	v_mfma_f32_16x16x32_bf16 v[70:73], v[150:153], v[242:245], v[70:73]
	v_mfma_f32_16x16x32_bf16 v[66:69], v[158:161], v[242:245], v[66:69]
	s_setprio 0
	s_add_i32 s24, s55, s23
	s_mov_b32 m0, s24
	ds_read_b128 v[192:195], v227 offset:49152
	ds_read_b128 v[196:199], v227 offset:50176
	ds_read_b128 v[200:203], v227 offset:51200
	ds_read_b128 v[204:207], v227 offset:52224
	ds_read_b128 v[230:233], v227 offset:53248
	ds_read_b128 v[234:237], v227 offset:54272
	ds_read_b128 v[238:241], v227 offset:55296
	ds_read_b128 v[242:245], v227 offset:56320
	s_add_u32 s98, s86, 0x80
	s_addc_u32 s99, s87, 0
	global_load_lds_dwordx4 v168, s[98:99]
	s_add_i32 m0, s24, 0x2000
	s_add_u32 s24, s86, 0x80080
	s_addc_u32 s25, s87, 0
	s_add_i32 s36, s36, s23
	s_add_u32 s100, s86, 0x80
	s_addc_u32 s101, s87, 0
	global_load_lds_dwordx4 v164, s[100:101]
	s_mov_b32 m0, s36
	s_nop 0
	global_load_lds_dwordx4 v168, s[24:25]
	s_add_i32 m0, s36, 0x2000
	s_nop 0
	global_load_lds_dwordx4 v164, s[24:25]
	s_mov_b32 m0, s15
	s_nop 0
	s_add_u32 s98, s88, 0x80
	s_addc_u32 s99, s89, 0
	global_load_lds_dwordx4 v170, s[98:99]
	s_mov_b32 m0, s26
	s_nop 0
	s_add_u32 s100, s88, 0x80
	s_addc_u32 s101, s89, 0
	global_load_lds_dwordx4 v166, s[100:101]
	s_waitcnt vmcnt(8)
	s_waitcnt lgkmcnt(0)
	s_barrier
	s_setprio 3
	s_waitcnt lgkmcnt(0)
	v_mfma_f32_16x16x32_bf16 v[62:65], v[130:133], v[192:195], v[62:65]
	v_mfma_f32_16x16x32_bf16 v[58:61], v[138:141], v[192:195], v[58:61]
	v_mfma_f32_16x16x32_bf16 v[46:49], v[130:133], v[200:203], v[46:49]
	v_mfma_f32_16x16x32_bf16 v[42:45], v[138:141], v[200:203], v[42:45]
	v_mfma_f32_16x16x32_bf16 v[30:33], v[130:133], v[230:233], v[30:33]
	v_mfma_f32_16x16x32_bf16 v[26:29], v[138:141], v[230:233], v[26:29]
	v_mfma_f32_16x16x32_bf16 v[14:17], v[130:133], v[238:241], v[14:17]
	v_mfma_f32_16x16x32_bf16 v[10:13], v[138:141], v[238:241], v[10:13]
	v_mfma_f32_16x16x32_bf16 v[62:65], v[134:137], v[196:199], v[62:65]
	v_mfma_f32_16x16x32_bf16 v[58:61], v[142:145], v[196:199], v[58:61]
	v_mfma_f32_16x16x32_bf16 v[46:49], v[134:137], v[204:207], v[46:49]
	v_mfma_f32_16x16x32_bf16 v[42:45], v[142:145], v[204:207], v[42:45]
	v_mfma_f32_16x16x32_bf16 v[30:33], v[134:137], v[234:237], v[30:33]
	v_mfma_f32_16x16x32_bf16 v[26:29], v[142:145], v[234:237], v[26:29]
	v_mfma_f32_16x16x32_bf16 v[14:17], v[134:137], v[242:245], v[14:17]
	v_mfma_f32_16x16x32_bf16 v[10:13], v[142:145], v[242:245], v[10:13]


; #define PG8_WAIT_V(n) asm volatile("s_waitcnt vmcnt(" #n ")" ::: "memory")
; #define PG8_WAIT_L(n) asm volatile("s_waitcnt lgkmcnt(" #n ")" ::: "memory")
; #define PG8_BAR __builtin_amdgcn_s_barrier()
; #define PG8_SCHED __builtin_amdgcn_sched_barrier(0)
; template <class Epi, class Sched, bool ALIGN_EPI = false, bool SP2 = false, bool F8 = false>
; __device__ __forceinline__ void gemm_phase(PG8_LAS unsigned char* lds, const Gemm g, const Sched& S, const Epi& E) {
;     ...
;         for (int t = 0; t < nt; t += 2) {
;     ...
;             PG8_WAIT_V(8); PG8_WAIT_L(0); PG8_BAR; PG8_MMA(1, 0, At, B0); PG8_MMA(1, 1, At, B1); PG8_BAR; PG8_SCHED;
	v_mfma_f32_16x16x32_bf16 v[54:57], v[146:149], v[192:195], v[54:57]
	v_mfma_f32_16x16x32_bf16 v[50:53], v[154:157], v[192:195], v[50:53]
	v_mfma_f32_16x16x32_bf16 v[38:41], v[146:149], v[200:203], v[38:41]
	v_mfma_f32_16x16x32_bf16 v[34:37], v[154:157], v[200:203], v[34:37]
	v_mfma_f32_16x16x32_bf16 v[22:25], v[146:149], v[230:233], v[22:25]
	v_mfma_f32_16x16x32_bf16 v[18:21], v[154:157], v[230:233], v[18:21]
	v_mfma_f32_16x16x32_bf16 v[6:9], v[146:149], v[238:241], v[6:9]
	v_mfma_f32_16x16x32_bf16 v[2:5], v[154:157], v[238:241], v[2:5]
	v_mfma_f32_16x16x32_bf16 v[54:57], v[150:153], v[196:199], v[54:57]
	v_mfma_f32_16x16x32_bf16 v[50:53], v[158:161], v[196:199], v[50:53]
	v_mfma_f32_16x16x32_bf16 v[38:41], v[150:153], v[204:207], v[38:41]
	v_mfma_f32_16x16x32_bf16 v[34:37], v[158:161], v[204:207], v[34:37]
	v_mfma_f32_16x16x32_bf16 v[22:25], v[150:153], v[234:237], v[22:25]
	v_mfma_f32_16x16x32_bf16 v[18:21], v[158:161], v[234:237], v[18:21]
	v_mfma_f32_16x16x32_bf16 v[6:9], v[150:153], v[242:245], v[6:9]
	v_mfma_f32_16x16x32_bf16 v[2:5], v[158:161], v[242:245], v[2:5]
	s_setprio 0
	s_add_i32 s54, s54, 2
	s_add_u32 s84, s84, 0x100
	s_addc_u32 s85, s85, 0
	s_add_u32 vcc_lo, vcc_lo, 0x100
	s_addc_u32 vcc_hi, vcc_hi, 0
	s_cmp_gt_u32 s54, 29
	s_cbranch_scc0 .Lk0_Y

; #define PG8_STAGE(bufoff, gbase, voff) do { _Pragma("unroll") for (int _i = 0; _i < 2; ++_i) \
;         __builtin_amdgcn_global_load_lds((const unsigned*)((const char*)(gbase) + (voff)[_i]), (PG8_LAS unsigned*)(lds + (bufoff) + ldsw + _i * 8192), 16, 0, 0); } while (0)
; #define PG8_LDA(dst, b, h) do { _Pragma("unroll") for (int m = 0; m < 4; ++m) _Pragma("unroll") for (int k = 0; k < 2; ++k) dst[m][k] = *(const PG8_LAS bf16x8*)(lds + PG8_SA(b, h) + aoff + m * 2048 + k * 1024); } while (0)
; #define PG8_LDB(dst, b, h) do { _Pragma("unroll") for (int n = 0; n < 2; ++n) _Pragma("unroll") for (int k = 0; k < 2; ++k) dst[n][k] = *(const PG8_LAS bf16x8*)(lds + PG8_SB(b, h) + boff + n * 2048 + k * 1024); } while (0)
; #define PG8_WAIT_V(n) asm volatile("s_waitcnt vmcnt(" #n ")" ::: "memory")
; #define PG8_WAIT_L(n) asm volatile("s_waitcnt lgkmcnt(" #n ")" ::: "memory")
; #define PG8_BAR __builtin_amdgcn_s_barrier()
; #define PG8_SCHED __builtin_amdgcn_sched_barrier(0)
; template <class Epi, class Sched, bool ALIGN_EPI = false, bool SP2 = false, bool F8 = false>
; __device__ __forceinline__ void gemm_phase(PG8_LAS unsigned char* lds, const Gemm g, const Sched& S, const Epi& E) {
;     ...
;             PG8_LDB(B0, 0, 0); PG8_LDB(B1, 0, 1); PG8_SCHED; PG8_LDA(At, 0, 0); PG8_STAGE(PG8_SA(1, 1), a1 + hstepA, voffA);
;             PG8_WAIT_V(8); PG8_WAIT_L(0); PG8_BAR; PG8_MMA(0, 0, At, B0); PG8_MMA(0, 1, At, B1); PG8_BAR; PG8_SCHED;
.Lk1_Y:
	ds_read_b128 v[26:29], v195
	ds_read_b128 v[30:33], v195 offset:1024
	ds_read_b128 v[18:21], v195 offset:2048
	ds_read_b128 v[22:25], v195 offset:3072
	ds_read_b128 v[10:13], v196
	ds_read_b128 v[14:17], v196 offset:1024
	ds_read_b128 v[2:5], v196 offset:2048
	ds_read_b128 v[6:9], v196 offset:3072
	s_add_u32 s24, s72, 0xfffc0080
	s_addc_u32 s25, s73, -1
	s_cmp_eq_u32 s87, 12
	s_cselect_b32 s77, s7, s25
	s_cselect_b32 s76, s65, s24
	s_cselect_b32 s75, s63, s86
	s_cselect_b32 s74, s71, s85
	s_add_i32 m0, s26, 0xc000
	ds_read_b128 v[182:185], v197
	ds_read_b128 v[186:189], v197 offset:1024
	ds_read_b128 v[200:203], v197 offset:2048
	ds_read_b128 v[204:207], v197 offset:3072
	ds_read_b128 v[208:211], v197 offset:4096
	ds_read_b128 v[212:215], v197 offset:5120
	ds_read_b128 v[218:221], v197 offset:6144
	ds_read_b128 v[222:225], v197 offset:7168
	global_load_lds_dwordx4 v178, s[72:73]
	s_add_i32 m0, s26, 0xe000
	s_nop 0
	global_load_lds_dwordx4 v180, s[72:73]
	s_waitcnt vmcnt(8)
	s_waitcnt lgkmcnt(0)
	s_barrier
	s_setprio 3
	s_waitcnt lgkmcnt(0)
	v_mfma_f32_16x16x128_f8f6f4 v[158:161], v[26:33], v[182:189], v[158:161]
	v_mfma_f32_16x16x128_f8f6f4 v[154:157], v[18:25], v[182:189], v[154:157]
	v_mfma_f32_16x16x128_f8f6f4 v[142:145], v[26:33], v[200:207], v[142:145]
	v_mfma_f32_16x16x128_f8f6f4 v[138:141], v[18:25], v[200:207], v[138:141]
	v_mfma_f32_16x16x128_f8f6f4 v[126:129], v[26:33], v[208:215], v[126:129]
	v_mfma_f32_16x16x128_f8f6f4 v[122:125], v[18:25], v[208:215], v[122:125]
	v_mfma_f32_16x16x128_f8f6f4 v[110:113], v[26:33], v[218:225], v[110:113]
	v_mfma_f32_16x16x128_f8f6f4 v[106:109], v[18:25], v[218:225], v[106:109]


; #define PG8_STAGE(bufoff, gbase, voff) do { _Pragma("unroll") for (int _i = 0; _i < 2; ++_i) \
;         __builtin_amdgcn_global_load_lds((const unsigned*)((const char*)(gbase) + (voff)[_i]), (PG8_LAS unsigned*)(lds + (bufoff) + ldsw + _i * 8192), 16, 0, 0); } while (0)
; #define PG8_LDA(dst, b, h) do { _Pragma("unroll") for (int m = 0; m < 4; ++m) _Pragma("unroll") for (int k = 0; k < 2; ++k) dst[m][k] = *(const PG8_LAS bf16x8*)(lds + PG8_SA(b, h) + aoff + m * 2048 + k * 1024); } while (0)
; #define PG8_WAIT_V(n) asm volatile("s_waitcnt vmcnt(" #n ")" ::: "memory")
; #define PG8_WAIT_L(n) asm volatile("s_waitcnt lgkmcnt(" #n ")" ::: "memory")
; #define PG8_BAR __builtin_amdgcn_s_barrier()
; #define PG8_SCHED __builtin_amdgcn_sched_barrier(0)
; template <class Epi, class Sched, bool ALIGN_EPI = false, bool SP2 = false, bool F8 = false>
; __device__ __forceinline__ void gemm_phase(PG8_LAS unsigned char* lds, const Gemm g, const Sched& S, const Epi& E) {
;     ...
;             PG8_WAIT_V(8); PG8_WAIT_L(0); PG8_BAR; PG8_MMA(0, 0, At, B0); PG8_MMA(0, 1, At, B1); PG8_BAR; PG8_SCHED;
;             PG8_LDA(At, 0, 1); PG8_STAGE(PG8_SB(0, 0), b2, voffB); PG8_STAGE(PG8_SB(0, 1), b2 + hstep, voffB); PG8_STAGE(PG8_SA(0, 0), a2, voffA);
;             PG8_WAIT_V(8); PG8_WAIT_L(0); PG8_BAR; PG8_MMA(1, 0, At, B0); PG8_MMA(1, 1, At, B1); PG8_BAR; PG8_SCHED;
	v_mfma_f32_16x16x128_f8f6f4 v[150:153], v[10:17], v[182:189], v[150:153]
	v_mfma_f32_16x16x128_f8f6f4 v[146:149], v[2:9], v[182:189], v[146:149]
	v_mfma_f32_16x16x128_f8f6f4 v[134:137], v[10:17], v[200:207], v[134:137]
	v_mfma_f32_16x16x128_f8f6f4 v[130:133], v[2:9], v[200:207], v[130:133]
	v_mfma_f32_16x16x128_f8f6f4 v[118:121], v[10:17], v[208:215], v[118:121]
	v_mfma_f32_16x16x128_f8f6f4 v[114:117], v[2:9], v[208:215], v[114:117]
	v_mfma_f32_16x16x128_f8f6f4 v[102:105], v[10:17], v[218:225], v[102:105]
	v_mfma_f32_16x16x128_f8f6f4 v[98:101], v[2:9], v[218:225], v[98:101]
	s_setprio 0
	s_add_i32 s24, s81, s14
	s_mov_b32 m0, s24
	ds_read_b128 v[200:203], v197 offset:16384
	ds_read_b128 v[204:207], v197 offset:17408
	ds_read_b128 v[208:211], v197 offset:18432
	ds_read_b128 v[212:215], v197 offset:19456
	ds_read_b128 v[218:221], v197 offset:20480
	ds_read_b128 v[222:225], v197 offset:21504
	ds_read_b128 v[226:229], v197 offset:22528
	ds_read_b128 v[230:233], v197 offset:23552
	global_load_lds_dwordx4 v166, s[74:75]
	s_add_i32 m0, s24, 0x2000
	s_add_u32 s24, s74, 0x40000
	s_addc_u32 s25, s75, 0
	s_add_i32 s36, s82, s14
	global_load_lds_dwordx4 v170, s[74:75]
	s_mov_b32 m0, s36
	s_nop 0
	global_load_lds_dwordx4 v166, s[24:25]
	s_add_i32 m0, s36, 0x2000
	s_nop 0
	global_load_lds_dwordx4 v170, s[24:25]
	s_mov_b32 m0, s26
	s_nop 0
	global_load_lds_dwordx4 v164, s[76:77]
	s_mov_b32 m0, s27
	s_nop 0
	global_load_lds_dwordx4 v168, s[76:77]
	s_waitcnt vmcnt(8)
	s_waitcnt lgkmcnt(0)
	s_barrier
	s_setprio 3
	s_waitcnt lgkmcnt(0)
	v_mfma_f32_16x16x128_f8f6f4 v[94:97], v[26:33], v[200:207], v[94:97]
	v_mfma_f32_16x16x128_f8f6f4 v[90:93], v[18:25], v[200:207], v[90:93]
	v_mfma_f32_16x16x128_f8f6f4 v[78:81], v[26:33], v[208:215], v[78:81]
	v_mfma_f32_16x16x128_f8f6f4 v[74:77], v[18:25], v[208:215], v[74:77]
	v_mfma_f32_16x16x128_f8f6f4 v[62:65], v[26:33], v[218:225], v[62:65]
	v_mfma_f32_16x16x128_f8f6f4 v[58:61], v[18:25], v[218:225], v[58:61]
	v_mfma_f32_16x16x128_f8f6f4 v[46:49], v[26:33], v[226:233], v[46:49]
	v_mfma_f32_16x16x128_f8f6f4 v[42:45], v[18:25], v[226:233], v[42:45]


; #define PG8_STAGE(bufoff, gbase, voff) do { _Pragma("unroll") for (int _i = 0; _i < 2; ++_i) \
;         __builtin_amdgcn_global_load_lds((const unsigned*)((const char*)(gbase) + (voff)[_i]), (PG8_LAS unsigned*)(lds + (bufoff) + ldsw + _i * 8192), 16, 0, 0); } while (0)
; #define PG8_LDA(dst, b, h) do { _Pragma("unroll") for (int m = 0; m < 4; ++m) _Pragma("unroll") for (int k = 0; k < 2; ++k) dst[m][k] = *(const PG8_LAS bf16x8*)(lds + PG8_SA(b, h) + aoff + m * 2048 + k * 1024); } while (0)
; #define PG8_LDB(dst, b, h) do { _Pragma("unroll") for (int n = 0; n < 2; ++n) _Pragma("unroll") for (int k = 0; k < 2; ++k) dst[n][k] = *(const PG8_LAS bf16x8*)(lds + PG8_SB(b, h) + boff + n * 2048 + k * 1024); } while (0)
; #define PG8_WAIT_V(n) asm volatile("s_waitcnt vmcnt(" #n ")" ::: "memory")
; #define PG8_WAIT_L(n) asm volatile("s_waitcnt lgkmcnt(" #n ")" ::: "memory")
; #define PG8_BAR __builtin_amdgcn_s_barrier()
; #define PG8_SCHED __builtin_amdgcn_sched_barrier(0)
; template <class Epi, class Sched, bool ALIGN_EPI = false, bool SP2 = false, bool F8 = false>
; __device__ __forceinline__ void gemm_phase(PG8_LAS unsigned char* lds, const Gemm g, const Sched& S, const Epi& E) {
;     ...
;             PG8_WAIT_V(8); PG8_WAIT_L(0); PG8_BAR; PG8_MMA(1, 0, At, B0); PG8_MMA(1, 1, At, B1); PG8_BAR; PG8_SCHED;
;             PG8_LDB(B0, 1, 0); PG8_LDB(B1, 1, 1); PG8_SCHED; PG8_LDA(At, 1, 0); PG8_STAGE(PG8_SA(0, 1), a2 + hstepA, voffA);
;             PG8_WAIT_V(8); PG8_WAIT_L(0); PG8_BAR; PG8_MMA(0, 0, At, B0); PG8_MMA(0, 1, At, B1); PG8_BAR; PG8_SCHED;
	v_mfma_f32_16x16x128_f8f6f4 v[86:89], v[10:17], v[200:207], v[86:89]
	v_mfma_f32_16x16x128_f8f6f4 v[82:85], v[2:9], v[200:207], v[82:85]
	v_mfma_f32_16x16x128_f8f6f4 v[70:73], v[10:17], v[208:215], v[70:73]
	v_mfma_f32_16x16x128_f8f6f4 v[66:69], v[2:9], v[208:215], v[66:69]
	v_mfma_f32_16x16x128_f8f6f4 v[54:57], v[10:17], v[218:225], v[54:57]
	v_mfma_f32_16x16x128_f8f6f4 v[50:53], v[2:9], v[218:225], v[50:53]
	v_mfma_f32_16x16x128_f8f6f4 v[38:41], v[10:17], v[226:233], v[38:41]
	v_mfma_f32_16x16x128_f8f6f4 v[34:37], v[2:9], v[226:233], v[34:37]
	s_setprio 0
	s_add_i32 s36, 0, 0x18000
	s_add_i32 s37, 0, 0x1c000
	v_add_u32_e32 v14, s36, v190
	v_add_u32_e32 v30, s37, v190
	ds_read_b128 v[2:5], v14
	ds_read_b128 v[6:9], v14 offset:1024
	ds_read_b128 v[10:13], v14 offset:2048
	ds_read_b128 v[14:17], v14 offset:3072
	ds_read_b128 v[18:21], v30
	ds_read_b128 v[22:25], v30 offset:1024
	ds_read_b128 v[26:29], v30 offset:2048
	ds_read_b128 v[30:33], v30 offset:3072
	s_add_u32 s24, s76, 0x40000
	s_addc_u32 s25, s77, 0
	s_mov_b32 m0, s28
	ds_read_b128 v[200:203], v197 offset:32768
	ds_read_b128 v[204:207], v197 offset:33792
	ds_read_b128 v[208:211], v197 offset:34816
	ds_read_b128 v[212:215], v197 offset:35840
	ds_read_b128 v[218:221], v197 offset:36864
	ds_read_b128 v[222:225], v197 offset:37888
	ds_read_b128 v[226:229], v197 offset:38912
	ds_read_b128 v[230:233], v197 offset:39936
	global_load_lds_dwordx4 v164, s[24:25]
	s_mov_b32 m0, s29
	s_nop 0
	global_load_lds_dwordx4 v168, s[24:25]
	s_waitcnt vmcnt(8)
	s_waitcnt lgkmcnt(0)
	s_barrier
	s_setprio 3
	s_waitcnt lgkmcnt(0)
	v_mfma_f32_16x16x128_f8f6f4 v[158:161], v[2:9], v[200:207], v[158:161]
	v_mfma_f32_16x16x128_f8f6f4 v[154:157], v[10:17], v[200:207], v[154:157]
	v_mfma_f32_16x16x128_f8f6f4 v[142:145], v[2:9], v[208:215], v[142:145]
	v_mfma_f32_16x16x128_f8f6f4 v[138:141], v[10:17], v[208:215], v[138:141]
	v_mfma_f32_16x16x128_f8f6f4 v[126:129], v[2:9], v[218:225], v[126:129]
	v_mfma_f32_16x16x128_f8f6f4 v[122:125], v[10:17], v[218:225], v[122:125]
	v_mfma_f32_16x16x128_f8f6f4 v[110:113], v[2:9], v[226:233], v[110:113]
	v_mfma_f32_16x16x128_f8f6f4 v[106:109], v[10:17], v[226:233], v[106:109]


; #define PG8_STAGE(bufoff, gbase, voff) do { _Pragma("unroll") for (int _i = 0; _i < 2; ++_i) \
;         __builtin_amdgcn_global_load_lds((const unsigned*)((const char*)(gbase) + (voff)[_i]), (PG8_LAS unsigned*)(lds + (bufoff) + ldsw + _i * 8192), 16, 0, 0); } while (0)
; #define PG8_LDA(dst, b, h) do { _Pragma("unroll") for (int m = 0; m < 4; ++m) _Pragma("unroll") for (int k = 0; k < 2; ++k) dst[m][k] = *(const PG8_LAS bf16x8*)(lds + PG8_SA(b, h) + aoff + m * 2048 + k * 1024); } while (0)
; #define PG8_WAIT_V(n) asm volatile("s_waitcnt vmcnt(" #n ")" ::: "memory")
; #define PG8_WAIT_L(n) asm volatile("s_waitcnt lgkmcnt(" #n ")" ::: "memory")
; #define PG8_BAR __builtin_amdgcn_s_barrier()
; #define PG8_SCHED __builtin_amdgcn_sched_barrier(0)
; template <class Epi, class Sched, bool ALIGN_EPI = false, bool SP2 = false, bool F8 = false>
; __device__ __forceinline__ void gemm_phase(PG8_LAS unsigned char* lds, const Gemm g, const Sched& S, const Epi& E) {
;     ...
;             PG8_WAIT_V(8); PG8_WAIT_L(0); PG8_BAR; PG8_MMA(0, 0, At, B0); PG8_MMA(0, 1, At, B1); PG8_BAR; PG8_SCHED;
;             PG8_LDA(At, 1, 1); PG8_STAGE(PG8_SB(1, 0), b3, voffB); PG8_STAGE(PG8_SB(1, 1), b3 + hstep, voffB); PG8_STAGE(PG8_SA(1, 0), a3, voffA);
;             PG8_WAIT_V(8); PG8_WAIT_L(0); PG8_BAR; PG8_MMA(1, 0, At, B0); PG8_MMA(1, 1, At, B1); PG8_BAR; PG8_SCHED;
	v_mfma_f32_16x16x128_f8f6f4 v[150:153], v[18:25], v[200:207], v[150:153]
	v_mfma_f32_16x16x128_f8f6f4 v[146:149], v[26:33], v[200:207], v[146:149]
	v_mfma_f32_16x16x128_f8f6f4 v[134:137], v[18:25], v[208:215], v[134:137]
	v_mfma_f32_16x16x128_f8f6f4 v[130:133], v[26:33], v[208:215], v[130:133]
	v_mfma_f32_16x16x128_f8f6f4 v[118:121], v[18:25], v[218:225], v[118:121]
	v_mfma_f32_16x16x128_f8f6f4 v[114:117], v[26:33], v[218:225], v[114:117]
	v_mfma_f32_16x16x128_f8f6f4 v[102:105], v[18:25], v[226:233], v[102:105]
	v_mfma_f32_16x16x128_f8f6f4 v[98:101], v[26:33], v[226:233], v[98:101]
	s_setprio 0
	s_add_i32 s24, s36, s14
	s_mov_b32 m0, s24
	ds_read_b128 v[200:203], v197 offset:49152
	ds_read_b128 v[204:207], v197 offset:50176
	ds_read_b128 v[208:211], v197 offset:51200
	ds_read_b128 v[212:215], v197 offset:52224
	ds_read_b128 v[218:221], v197 offset:53248
	ds_read_b128 v[222:225], v197 offset:54272
	ds_read_b128 v[226:229], v197 offset:55296
	ds_read_b128 v[230:233], v197 offset:56320
	s_add_u32 s98, s74, 0x80
	s_addc_u32 s99, s75, 0
	global_load_lds_dwordx4 v166, s[98:99]
	s_add_i32 m0, s24, 0x2000
	s_add_u32 s24, s74, 0x40080
	s_addc_u32 s25, s75, 0
	s_add_i32 s36, s37, s14
	s_add_u32 s100, s74, 0x80
	s_addc_u32 s101, s75, 0
	global_load_lds_dwordx4 v170, s[100:101]
	s_mov_b32 m0, s36
	s_nop 0
	global_load_lds_dwordx4 v166, s[24:25]
	s_add_i32 m0, s36, 0x2000
	s_nop 0
	global_load_lds_dwordx4 v170, s[24:25]
	s_mov_b32 m0, s45
	s_nop 0
	s_add_u32 s98, s76, 0x80
	s_addc_u32 s99, s77, 0
	global_load_lds_dwordx4 v164, s[98:99]
	s_mov_b32 m0, s78
	s_nop 0
	s_add_u32 s100, s76, 0x80
	s_addc_u32 s101, s77, 0
	global_load_lds_dwordx4 v168, s[100:101]
	s_waitcnt vmcnt(8)
	s_waitcnt lgkmcnt(0)
	s_barrier
	s_setprio 3
	s_waitcnt lgkmcnt(0)
	v_mfma_f32_16x16x128_f8f6f4 v[94:97], v[2:9], v[200:207], v[94:97]
	v_mfma_f32_16x16x128_f8f6f4 v[90:93], v[10:17], v[200:207], v[90:93]
	v_mfma_f32_16x16x128_f8f6f4 v[78:81], v[2:9], v[208:215], v[78:81]
	v_mfma_f32_16x16x128_f8f6f4 v[74:77], v[10:17], v[208:215], v[74:77]
	v_mfma_f32_16x16x128_f8f6f4 v[62:65], v[2:9], v[218:225], v[62:65]
	v_mfma_f32_16x16x128_f8f6f4 v[58:61], v[10:17], v[218:225], v[58:61]
	v_mfma_f32_16x16x128_f8f6f4 v[46:49], v[2:9], v[226:233], v[46:49]
	v_mfma_f32_16x16x128_f8f6f4 v[42:45], v[10:17], v[226:233], v[42:45]


; #define PG8_WAIT_V(n) asm volatile("s_waitcnt vmcnt(" #n ")" ::: "memory")
; #define PG8_WAIT_L(n) asm volatile("s_waitcnt lgkmcnt(" #n ")" ::: "memory")
; #define PG8_BAR __builtin_amdgcn_s_barrier()
; #define PG8_SCHED __builtin_amdgcn_sched_barrier(0)
; template <class Epi, class Sched, bool ALIGN_EPI = false, bool SP2 = false, bool F8 = false>
; __device__ __forceinline__ void gemm_phase(PG8_LAS unsigned char* lds, const Gemm g, const Sched& S, const Epi& E) {
;     ...
;         for (int t = 0; t < nt; t += 2) {
;     ...
;             PG8_WAIT_V(8); PG8_WAIT_L(0); PG8_BAR; PG8_MMA(1, 0, At, B0); PG8_MMA(1, 1, At, B1); PG8_BAR; PG8_SCHED;
	v_mfma_f32_16x16x128_f8f6f4 v[86:89], v[18:25], v[200:207], v[86:89]
	v_mfma_f32_16x16x128_f8f6f4 v[82:85], v[26:33], v[200:207], v[82:85]
	v_mfma_f32_16x16x128_f8f6f4 v[70:73], v[18:25], v[208:215], v[70:73]
	v_mfma_f32_16x16x128_f8f6f4 v[66:69], v[26:33], v[208:215], v[66:69]
	v_mfma_f32_16x16x128_f8f6f4 v[54:57], v[18:25], v[218:225], v[54:57]
	v_mfma_f32_16x16x128_f8f6f4 v[50:53], v[26:33], v[218:225], v[50:53]
	v_mfma_f32_16x16x128_f8f6f4 v[38:41], v[18:25], v[226:233], v[38:41]
	v_mfma_f32_16x16x128_f8f6f4 v[34:37], v[26:33], v[226:233], v[34:37]
	s_setprio 0
	s_add_i32 s87, s87, 2
	s_add_u32 s72, s72, 0x100
	s_addc_u32 s73, s73, 0
	s_add_u32 s85, s85, 0x100
	s_addc_u32 s86, s86, 0
	s_cmp_gt_u32 s87, 13
	s_cbranch_scc0 .Lk1_Y

; #define PG8_STAGE(bufoff, gbase, voff) do { _Pragma("unroll") for (int _i = 0; _i < 2; ++_i) \
;         __builtin_amdgcn_global_load_lds((const unsigned*)((const char*)(gbase) + (voff)[_i]), (PG8_LAS unsigned*)(lds + (bufoff) + ldsw + _i * 8192), 16, 0, 0); } while (0)
; #define PG8_LDA(dst, b, h) do { _Pragma("unroll") for (int m = 0; m < 4; ++m) _Pragma("unroll") for (int k = 0; k < 2; ++k) dst[m][k] = *(const PG8_LAS bf16x8*)(lds + PG8_SA(b, h) + aoff + m * 2048 + k * 1024); } while (0)
; #define PG8_LDB(dst, b, h) do { _Pragma("unroll") for (int n = 0; n < 2; ++n) _Pragma("unroll") for (int k = 0; k < 2; ++k) dst[n][k] = *(const PG8_LAS bf16x8*)(lds + PG8_SB(b, h) + boff + n * 2048 + k * 1024); } while (0)
; #define PG8_WAIT_V(n) asm volatile("s_waitcnt vmcnt(" #n ")" ::: "memory")
; #define PG8_WAIT_L(n) asm volatile("s_waitcnt lgkmcnt(" #n ")" ::: "memory")
; #define PG8_BAR __builtin_amdgcn_s_barrier()
; #define PG8_SCHED __builtin_amdgcn_sched_barrier(0)
; template <class Epi, class Sched, bool ALIGN_EPI = false, bool SP2 = false, bool F8 = false>
; __device__ __forceinline__ void gemm_phase(PG8_LAS unsigned char* lds, const Gemm g, const Sched& S, const Epi& E) {
;     ...
;             PG8_LDB(B0, 0, 0); PG8_LDB(B1, 0, 1); PG8_SCHED; PG8_LDA(At, 0, 0); PG8_STAGE(PG8_SA(1, 1), a1 + hstepA, voffA);
;             PG8_WAIT_V(8); PG8_WAIT_L(0); PG8_BAR; PG8_MMA(0, 0, At, B0); PG8_MMA(0, 1, At, B1); PG8_BAR; PG8_SCHED;
.Lk2_Y:
	ds_read_b128 v[82:85], v204
	ds_read_b128 v[86:89], v204 offset:1024
	ds_read_b128 v[90:93], v204 offset:2048
	ds_read_b128 v[94:97], v204 offset:3072
	ds_read_b128 v[102:105], v205
	ds_read_b128 v[106:109], v205 offset:1024
	ds_read_b128 v[114:117], v205 offset:2048
	ds_read_b128 v[118:121], v205 offset:3072
	s_add_u32 s24, s62, 0xfff80080
	s_addc_u32 s25, s63, -1
	s_cmp_eq_u32 s76, 28
	s_cselect_b32 s67, s55, s25
	s_cselect_b32 s66, s61, s24
	s_cselect_b32 s65, s53, s75
	s_cselect_b32 s64, s73, s74
	s_add_i32 m0, s15, 0xc000
	ds_read_b128 v[162:165], v206
	ds_read_b128 v[166:169], v206 offset:1024
	ds_read_b128 v[170:173], v206 offset:2048
	ds_read_b128 v[174:177], v206 offset:3072
	ds_read_b128 v[194:197], v206 offset:4096
	ds_read_b128 v[198:201], v206 offset:5120
	ds_read_b128 v[208:211], v206 offset:6144
	ds_read_b128 v[212:215], v206 offset:7168
	global_load_lds_dwordx4 v186, s[62:63]
	s_add_i32 m0, s15, 0xe000
	s_nop 0
	global_load_lds_dwordx4 v188, s[62:63]
	s_waitcnt vmcnt(8)
	s_waitcnt lgkmcnt(0)
	s_barrier
	s_setprio 3
	s_waitcnt lgkmcnt(0)
	v_mfma_f32_16x16x32_bf16 v[158:161], v[82:85], v[162:165], v[158:161]
	v_mfma_f32_16x16x32_bf16 v[154:157], v[90:93], v[162:165], v[154:157]
	v_mfma_f32_16x16x32_bf16 v[142:145], v[82:85], v[170:173], v[142:145]
	v_mfma_f32_16x16x32_bf16 v[138:141], v[90:93], v[170:173], v[138:141]
	v_mfma_f32_16x16x32_bf16 v[126:129], v[82:85], v[194:197], v[126:129]
	v_mfma_f32_16x16x32_bf16 v[122:125], v[90:93], v[194:197], v[122:125]
	v_mfma_f32_16x16x32_bf16 v[78:81], v[82:85], v[208:211], v[78:81]
	v_mfma_f32_16x16x32_bf16 v[74:77], v[90:93], v[208:211], v[74:77]
	v_mfma_f32_16x16x32_bf16 v[158:161], v[86:89], v[166:169], v[158:161]
	v_mfma_f32_16x16x32_bf16 v[154:157], v[94:97], v[166:169], v[154:157]
	v_mfma_f32_16x16x32_bf16 v[142:145], v[86:89], v[174:177], v[142:145]
	v_mfma_f32_16x16x32_bf16 v[138:141], v[94:97], v[174:177], v[138:141]
	v_mfma_f32_16x16x32_bf16 v[126:129], v[86:89], v[198:201], v[126:129]
	v_mfma_f32_16x16x32_bf16 v[122:125], v[94:97], v[198:201], v[122:125]
	v_mfma_f32_16x16x32_bf16 v[78:81], v[86:89], v[212:215], v[78:81]
	v_mfma_f32_16x16x32_bf16 v[74:77], v[94:97], v[212:215], v[74:77]


; #define PG8_STAGE(bufoff, gbase, voff) do { _Pragma("unroll") for (int _i = 0; _i < 2; ++_i) \
;         __builtin_amdgcn_global_load_lds((const unsigned*)((const char*)(gbase) + (voff)[_i]), (PG8_LAS unsigned*)(lds + (bufoff) + ldsw + _i * 8192), 16, 0, 0); } while (0)
; #define PG8_LDA(dst, b, h) do { _Pragma("unroll") for (int m = 0; m < 4; ++m) _Pragma("unroll") for (int k = 0; k < 2; ++k) dst[m][k] = *(const PG8_LAS bf16x8*)(lds + PG8_SA(b, h) + aoff + m * 2048 + k * 1024); } while (0)
; #define PG8_WAIT_V(n) asm volatile("s_waitcnt vmcnt(" #n ")" ::: "memory")
; #define PG8_WAIT_L(n) asm volatile("s_waitcnt lgkmcnt(" #n ")" ::: "memory")
; #define PG8_BAR __builtin_amdgcn_s_barrier()
; #define PG8_SCHED __builtin_amdgcn_sched_barrier(0)
; template <class Epi, class Sched, bool ALIGN_EPI = false, bool SP2 = false, bool F8 = false>
; __device__ __forceinline__ void gemm_phase(PG8_LAS unsigned char* lds, const Gemm g, const Sched& S, const Epi& E) {
;     ...
;             PG8_WAIT_V(8); PG8_WAIT_L(0); PG8_BAR; PG8_MMA(0, 0, At, B0); PG8_MMA(0, 1, At, B1); PG8_BAR; PG8_SCHED;
;             PG8_LDA(At, 0, 1); PG8_STAGE(PG8_SB(0, 0), b2, voffB); PG8_STAGE(PG8_SB(0, 1), b2 + hstep, voffB); PG8_STAGE(PG8_SA(0, 0), a2, voffA);
;             PG8_WAIT_V(8); PG8_WAIT_L(0); PG8_BAR; PG8_MMA(1, 0, At, B0); PG8_MMA(1, 1, At, B1); PG8_BAR; PG8_SCHED;
	v_mfma_f32_16x16x32_bf16 v[150:153], v[102:105], v[162:165], v[150:153]
	v_mfma_f32_16x16x32_bf16 v[146:149], v[114:117], v[162:165], v[146:149]
	v_mfma_f32_16x16x32_bf16 v[134:137], v[102:105], v[170:173], v[134:137]
	v_mfma_f32_16x16x32_bf16 v[130:133], v[114:117], v[170:173], v[130:133]
	v_mfma_f32_16x16x32_bf16 v[110:113], v[102:105], v[194:197], v[110:113]
	v_mfma_f32_16x16x32_bf16 v[98:101], v[114:117], v[194:197], v[98:101]
	v_mfma_f32_16x16x32_bf16 v[70:73], v[102:105], v[208:211], v[70:73]
	v_mfma_f32_16x16x32_bf16 v[66:69], v[114:117], v[208:211], v[66:69]
	v_mfma_f32_16x16x32_bf16 v[150:153], v[106:109], v[166:169], v[150:153]
	v_mfma_f32_16x16x32_bf16 v[146:149], v[118:121], v[166:169], v[146:149]
	v_mfma_f32_16x16x32_bf16 v[134:137], v[106:109], v[174:177], v[134:137]
	v_mfma_f32_16x16x32_bf16 v[130:133], v[118:121], v[174:177], v[130:133]
	v_mfma_f32_16x16x32_bf16 v[110:113], v[106:109], v[198:201], v[110:113]
	v_mfma_f32_16x16x32_bf16 v[98:101], v[118:121], v[198:201], v[98:101]
	v_mfma_f32_16x16x32_bf16 v[70:73], v[106:109], v[212:215], v[70:73]
	v_mfma_f32_16x16x32_bf16 v[66:69], v[118:121], v[212:215], v[66:69]
	s_setprio 0
	s_add_i32 s24, s70, s14
	s_mov_b32 m0, s24
	ds_read_b128 v[162:165], v206 offset:16384
	ds_read_b128 v[166:169], v206 offset:17408
	ds_read_b128 v[170:173], v206 offset:18432
	ds_read_b128 v[174:177], v206 offset:19456
	ds_read_b128 v[194:197], v206 offset:20480
	ds_read_b128 v[198:201], v206 offset:21504
	ds_read_b128 v[208:211], v206 offset:22528
	ds_read_b128 v[212:215], v206 offset:23552
	global_load_lds_dwordx4 v180, s[64:65]
	s_add_i32 m0, s24, 0x2000
	s_add_u32 s24, s64, 0x80000
	s_addc_u32 s25, s65, 0
	s_add_i32 s36, s71, s14
	global_load_lds_dwordx4 v184, s[64:65]
	s_mov_b32 m0, s36
	s_nop 0
	global_load_lds_dwordx4 v180, s[24:25]
	s_add_i32 m0, s36, 0x2000
	s_nop 0
	global_load_lds_dwordx4 v184, s[24:25]
	s_mov_b32 m0, s15
	s_nop 0
	global_load_lds_dwordx4 v178, s[66:67]
	s_mov_b32 m0, s23
	s_nop 0
	global_load_lds_dwordx4 v182, s[66:67]
	s_waitcnt vmcnt(8)
	s_waitcnt lgkmcnt(0)
	s_barrier
	s_setprio 3
	s_waitcnt lgkmcnt(0)
	v_mfma_f32_16x16x32_bf16 v[62:65], v[82:85], v[162:165], v[62:65]
	v_mfma_f32_16x16x32_bf16 v[58:61], v[90:93], v[162:165], v[58:61]
	v_mfma_f32_16x16x32_bf16 v[46:49], v[82:85], v[170:173], v[46:49]
	v_mfma_f32_16x16x32_bf16 v[42:45], v[90:93], v[170:173], v[42:45]
	v_mfma_f32_16x16x32_bf16 v[30:33], v[82:85], v[194:197], v[30:33]
	v_mfma_f32_16x16x32_bf16 v[26:29], v[90:93], v[194:197], v[26:29]
	v_mfma_f32_16x16x32_bf16 v[14:17], v[82:85], v[208:211], v[14:17]
	v_mfma_f32_16x16x32_bf16 v[10:13], v[90:93], v[208:211], v[10:13]
	v_mfma_f32_16x16x32_bf16 v[62:65], v[86:89], v[166:169], v[62:65]
	v_mfma_f32_16x16x32_bf16 v[58:61], v[94:97], v[166:169], v[58:61]
	v_mfma_f32_16x16x32_bf16 v[46:49], v[86:89], v[174:177], v[46:49]
	v_mfma_f32_16x16x32_bf16 v[42:45], v[94:97], v[174:177], v[42:45]
	v_mfma_f32_16x16x32_bf16 v[30:33], v[86:89], v[198:201], v[30:33]
	v_mfma_f32_16x16x32_bf16 v[26:29], v[94:97], v[198:201], v[26:29]
	v_mfma_f32_16x16x32_bf16 v[14:17], v[86:89], v[212:215], v[14:17]
	v_mfma_f32_16x16x32_bf16 v[10:13], v[94:97], v[212:215], v[10:13]


; #define PG8_STAGE(bufoff, gbase, voff) do { _Pragma("unroll") for (int _i = 0; _i < 2; ++_i) \
;         __builtin_amdgcn_global_load_lds((const unsigned*)((const char*)(gbase) + (voff)[_i]), (PG8_LAS unsigned*)(lds + (bufoff) + ldsw + _i * 8192), 16, 0, 0); } while (0)
; #define PG8_LDA(dst, b, h) do { _Pragma("unroll") for (int m = 0; m < 4; ++m) _Pragma("unroll") for (int k = 0; k < 2; ++k) dst[m][k] = *(const PG8_LAS bf16x8*)(lds + PG8_SA(b, h) + aoff + m * 2048 + k * 1024); } while (0)
; #define PG8_LDB(dst, b, h) do { _Pragma("unroll") for (int n = 0; n < 2; ++n) _Pragma("unroll") for (int k = 0; k < 2; ++k) dst[n][k] = *(const PG8_LAS bf16x8*)(lds + PG8_SB(b, h) + boff + n * 2048 + k * 1024); } while (0)
; #define PG8_WAIT_V(n) asm volatile("s_waitcnt vmcnt(" #n ")" ::: "memory")
; #define PG8_WAIT_L(n) asm volatile("s_waitcnt lgkmcnt(" #n ")" ::: "memory")
; #define PG8_BAR __builtin_amdgcn_s_barrier()
; #define PG8_SCHED __builtin_amdgcn_sched_barrier(0)
; template <class Epi, class Sched, bool ALIGN_EPI = false, bool SP2 = false, bool F8 = false>
; __device__ __forceinline__ void gemm_phase(PG8_LAS unsigned char* lds, const Gemm g, const Sched& S, const Epi& E) {
;     ...
;             PG8_WAIT_V(8); PG8_WAIT_L(0); PG8_BAR; PG8_MMA(1, 0, At, B0); PG8_MMA(1, 1, At, B1); PG8_BAR; PG8_SCHED;
;             PG8_LDB(B0, 1, 0); PG8_LDB(B1, 1, 1); PG8_SCHED; PG8_LDA(At, 1, 0); PG8_STAGE(PG8_SA(0, 1), a2 + hstepA, voffA);
;             PG8_WAIT_V(8); PG8_WAIT_L(0); PG8_BAR; PG8_MMA(0, 0, At, B0); PG8_MMA(0, 1, At, B1); PG8_BAR; PG8_SCHED;
	v_mfma_f32_16x16x32_bf16 v[54:57], v[102:105], v[162:165], v[54:57]
	v_mfma_f32_16x16x32_bf16 v[50:53], v[114:117], v[162:165], v[50:53]
	v_mfma_f32_16x16x32_bf16 v[38:41], v[102:105], v[170:173], v[38:41]
	v_mfma_f32_16x16x32_bf16 v[34:37], v[114:117], v[170:173], v[34:37]
	v_mfma_f32_16x16x32_bf16 v[22:25], v[102:105], v[194:197], v[22:25]
	v_mfma_f32_16x16x32_bf16 v[18:21], v[114:117], v[194:197], v[18:21]
	v_mfma_f32_16x16x32_bf16 v[6:9], v[102:105], v[208:211], v[6:9]
	v_mfma_f32_16x16x32_bf16 v[2:5], v[114:117], v[208:211], v[2:5]
	v_mfma_f32_16x16x32_bf16 v[54:57], v[106:109], v[166:169], v[54:57]
	v_mfma_f32_16x16x32_bf16 v[50:53], v[118:121], v[166:169], v[50:53]
	v_mfma_f32_16x16x32_bf16 v[38:41], v[106:109], v[174:177], v[38:41]
	v_mfma_f32_16x16x32_bf16 v[34:37], v[118:121], v[174:177], v[34:37]
	v_mfma_f32_16x16x32_bf16 v[22:25], v[106:109], v[198:201], v[22:25]
	v_mfma_f32_16x16x32_bf16 v[18:21], v[118:121], v[198:201], v[18:21]
	v_mfma_f32_16x16x32_bf16 v[6:9], v[106:109], v[212:215], v[6:9]
	v_mfma_f32_16x16x32_bf16 v[2:5], v[118:121], v[212:215], v[2:5]
	s_setprio 0
	s_add_i32 s36, 0, 0x18000
	s_add_i32 s37, 0, 0x1c000
	v_add_u32_e32 v94, s36, v202
	v_add_u32_e32 v118, s37, v202
	ds_read_b128 v[82:85], v94
	ds_read_b128 v[86:89], v94 offset:1024
	ds_read_b128 v[90:93], v94 offset:2048
	ds_read_b128 v[94:97], v94 offset:3072
	ds_read_b128 v[102:105], v118
	ds_read_b128 v[106:109], v118 offset:1024
	ds_read_b128 v[114:117], v118 offset:2048
	ds_read_b128 v[118:121], v118 offset:3072
	s_add_u32 s24, s66, 0x80000
	s_addc_u32 s25, s67, 0
	s_mov_b32 m0, s26
	ds_read_b128 v[162:165], v206 offset:32768
	ds_read_b128 v[166:169], v206 offset:33792
	ds_read_b128 v[170:173], v206 offset:34816
	ds_read_b128 v[174:177], v206 offset:35840
	ds_read_b128 v[194:197], v206 offset:36864
	ds_read_b128 v[198:201], v206 offset:37888
	ds_read_b128 v[208:211], v206 offset:38912
	ds_read_b128 v[212:215], v206 offset:39936
	global_load_lds_dwordx4 v178, s[24:25]
	s_mov_b32 m0, s27
	s_nop 0
	global_load_lds_dwordx4 v182, s[24:25]
	s_waitcnt vmcnt(8)
	s_waitcnt lgkmcnt(0)
	s_barrier
	s_setprio 3
	s_waitcnt lgkmcnt(0)
	v_mfma_f32_16x16x32_bf16 v[158:161], v[82:85], v[162:165], v[158:161]
	v_mfma_f32_16x16x32_bf16 v[154:157], v[90:93], v[162:165], v[154:157]
	v_mfma_f32_16x16x32_bf16 v[142:145], v[82:85], v[170:173], v[142:145]
	v_mfma_f32_16x16x32_bf16 v[138:141], v[90:93], v[170:173], v[138:141]
	v_mfma_f32_16x16x32_bf16 v[126:129], v[82:85], v[194:197], v[126:129]
	v_mfma_f32_16x16x32_bf16 v[122:125], v[90:93], v[194:197], v[122:125]
	v_mfma_f32_16x16x32_bf16 v[78:81], v[82:85], v[208:211], v[78:81]
	v_mfma_f32_16x16x32_bf16 v[74:77], v[90:93], v[208:211], v[74:77]
	v_mfma_f32_16x16x32_bf16 v[158:161], v[86:89], v[166:169], v[158:161]
	v_mfma_f32_16x16x32_bf16 v[154:157], v[94:97], v[166:169], v[154:157]
	v_mfma_f32_16x16x32_bf16 v[142:145], v[86:89], v[174:177], v[142:145]
	v_mfma_f32_16x16x32_bf16 v[138:141], v[94:97], v[174:177], v[138:141]
	v_mfma_f32_16x16x32_bf16 v[126:129], v[86:89], v[198:201], v[126:129]
	v_mfma_f32_16x16x32_bf16 v[122:125], v[94:97], v[198:201], v[122:125]
	v_mfma_f32_16x16x32_bf16 v[78:81], v[86:89], v[212:215], v[78:81]
	v_mfma_f32_16x16x32_bf16 v[74:77], v[94:97], v[212:215], v[74:77]


; #define PG8_STAGE(bufoff, gbase, voff) do { _Pragma("unroll") for (int _i = 0; _i < 2; ++_i) \
;         __builtin_amdgcn_global_load_lds((const unsigned*)((const char*)(gbase) + (voff)[_i]), (PG8_LAS unsigned*)(lds + (bufoff) + ldsw + _i * 8192), 16, 0, 0); } while (0)
; #define PG8_LDA(dst, b, h) do { _Pragma("unroll") for (int m = 0; m < 4; ++m) _Pragma("unroll") for (int k = 0; k < 2; ++k) dst[m][k] = *(const PG8_LAS bf16x8*)(lds + PG8_SA(b, h) + aoff + m * 2048 + k * 1024); } while (0)
; #define PG8_WAIT_V(n) asm volatile("s_waitcnt vmcnt(" #n ")" ::: "memory")
; #define PG8_WAIT_L(n) asm volatile("s_waitcnt lgkmcnt(" #n ")" ::: "memory")
; #define PG8_BAR __builtin_amdgcn_s_barrier()
; #define PG8_SCHED __builtin_amdgcn_sched_barrier(0)
; template <class Epi, class Sched, bool ALIGN_EPI = false, bool SP2 = false, bool F8 = false>
; __device__ __forceinline__ void gemm_phase(PG8_LAS unsigned char* lds, const Gemm g, const Sched& S, const Epi& E) {
;     ...
;             PG8_WAIT_V(8); PG8_WAIT_L(0); PG8_BAR; PG8_MMA(0, 0, At, B0); PG8_MMA(0, 1, At, B1); PG8_BAR; PG8_SCHED;
;             PG8_LDA(At, 1, 1); PG8_STAGE(PG8_SB(1, 0), b3, voffB); PG8_STAGE(PG8_SB(1, 1), b3 + hstep, voffB); PG8_STAGE(PG8_SA(1, 0), a3, voffA);
;             PG8_WAIT_V(8); PG8_WAIT_L(0); PG8_BAR; PG8_MMA(1, 0, At, B0); PG8_MMA(1, 1, At, B1); PG8_BAR; PG8_SCHED;
	v_mfma_f32_16x16x32_bf16 v[150:153], v[102:105], v[162:165], v[150:153]
	v_mfma_f32_16x16x32_bf16 v[146:149], v[114:117], v[162:165], v[146:149]
	v_mfma_f32_16x16x32_bf16 v[134:137], v[102:105], v[170:173], v[134:137]
	v_mfma_f32_16x16x32_bf16 v[130:133], v[114:117], v[170:173], v[130:133]
	v_mfma_f32_16x16x32_bf16 v[110:113], v[102:105], v[194:197], v[110:113]
	v_mfma_f32_16x16x32_bf16 v[98:101], v[114:117], v[194:197], v[98:101]
	v_mfma_f32_16x16x32_bf16 v[70:73], v[102:105], v[208:211], v[70:73]
	v_mfma_f32_16x16x32_bf16 v[66:69], v[114:117], v[208:211], v[66:69]
	v_mfma_f32_16x16x32_bf16 v[150:153], v[106:109], v[166:169], v[150:153]
	v_mfma_f32_16x16x32_bf16 v[146:149], v[118:121], v[166:169], v[146:149]
	v_mfma_f32_16x16x32_bf16 v[134:137], v[106:109], v[174:177], v[134:137]
	v_mfma_f32_16x16x32_bf16 v[130:133], v[118:121], v[174:177], v[130:133]
	v_mfma_f32_16x16x32_bf16 v[110:113], v[106:109], v[198:201], v[110:113]
	v_mfma_f32_16x16x32_bf16 v[98:101], v[118:121], v[198:201], v[98:101]
	v_mfma_f32_16x16x32_bf16 v[70:73], v[106:109], v[212:215], v[70:73]
	v_mfma_f32_16x16x32_bf16 v[66:69], v[118:121], v[212:215], v[66:69]
	s_setprio 0
	s_add_i32 s24, s36, s14
	s_mov_b32 m0, s24
	ds_read_b128 v[162:165], v206 offset:49152
	ds_read_b128 v[166:169], v206 offset:50176
	ds_read_b128 v[170:173], v206 offset:51200
	ds_read_b128 v[174:177], v206 offset:52224
	ds_read_b128 v[194:197], v206 offset:53248
	ds_read_b128 v[198:201], v206 offset:54272
	ds_read_b128 v[208:211], v206 offset:55296
	ds_read_b128 v[212:215], v206 offset:56320
	s_add_u32 s98, s64, 0x80
	s_addc_u32 s99, s65, 0
	global_load_lds_dwordx4 v180, s[98:99]
	s_add_i32 m0, s24, 0x2000
	s_add_u32 s24, s64, 0x80080
	s_addc_u32 s25, s65, 0
	s_add_i32 s36, s37, s14
	s_add_u32 s100, s64, 0x80
	s_addc_u32 s101, s65, 0
	global_load_lds_dwordx4 v184, s[100:101]
	s_mov_b32 m0, s36
	s_nop 0
	global_load_lds_dwordx4 v180, s[24:25]
	s_add_i32 m0, s36, 0x2000
	s_nop 0
	global_load_lds_dwordx4 v184, s[24:25]
	s_mov_b32 m0, s44
	s_nop 0
	s_add_u32 s98, s66, 0x80
	s_addc_u32 s99, s67, 0
	global_load_lds_dwordx4 v178, s[98:99]
	s_mov_b32 m0, s45
	s_nop 0
	s_add_u32 s100, s66, 0x80
	s_addc_u32 s101, s67, 0
	global_load_lds_dwordx4 v182, s[100:101]
	s_waitcnt vmcnt(8)
	s_waitcnt lgkmcnt(0)
	s_barrier
	s_setprio 3
	s_waitcnt lgkmcnt(0)
	v_mfma_f32_16x16x32_bf16 v[62:65], v[82:85], v[162:165], v[62:65]
	v_mfma_f32_16x16x32_bf16 v[58:61], v[90:93], v[162:165], v[58:61]
	v_mfma_f32_16x16x32_bf16 v[46:49], v[82:85], v[170:173], v[46:49]
	v_mfma_f32_16x16x32_bf16 v[42:45], v[90:93], v[170:173], v[42:45]
	v_mfma_f32_16x16x32_bf16 v[30:33], v[82:85], v[194:197], v[30:33]
	v_mfma_f32_16x16x32_bf16 v[26:29], v[90:93], v[194:197], v[26:29]
	v_mfma_f32_16x16x32_bf16 v[14:17], v[82:85], v[208:211], v[14:17]
	v_mfma_f32_16x16x32_bf16 v[10:13], v[90:93], v[208:211], v[10:13]
	v_mfma_f32_16x16x32_bf16 v[62:65], v[86:89], v[166:169], v[62:65]
	v_mfma_f32_16x16x32_bf16 v[58:61], v[94:97], v[166:169], v[58:61]
	v_mfma_f32_16x16x32_bf16 v[46:49], v[86:89], v[174:177], v[46:49]
	v_mfma_f32_16x16x32_bf16 v[42:45], v[94:97], v[174:177], v[42:45]
	v_mfma_f32_16x16x32_bf16 v[30:33], v[86:89], v[198:201], v[30:33]
	v_mfma_f32_16x16x32_bf16 v[26:29], v[94:97], v[198:201], v[26:29]
	v_mfma_f32_16x16x32_bf16 v[14:17], v[86:89], v[212:215], v[14:17]
	v_mfma_f32_16x16x32_bf16 v[10:13], v[94:97], v[212:215], v[10:13]


; #define PG8_WAIT_V(n) asm volatile("s_waitcnt vmcnt(" #n ")" ::: "memory")
; #define PG8_WAIT_L(n) asm volatile("s_waitcnt lgkmcnt(" #n ")" ::: "memory")
; #define PG8_BAR __builtin_amdgcn_s_barrier()
; #define PG8_SCHED __builtin_amdgcn_sched_barrier(0)
; template <class Epi, class Sched, bool ALIGN_EPI = false, bool SP2 = false, bool F8 = false>
; __device__ __forceinline__ void gemm_phase(PG8_LAS unsigned char* lds, const Gemm g, const Sched& S, const Epi& E) {
;     ...
;         for (int t = 0; t < nt; t += 2) {
;     ...
;             PG8_WAIT_V(8); PG8_WAIT_L(0); PG8_BAR; PG8_MMA(1, 0, At, B0); PG8_MMA(1, 1, At, B1); PG8_BAR; PG8_SCHED;
	v_mfma_f32_16x16x32_bf16 v[54:57], v[102:105], v[162:165], v[54:57]
	v_mfma_f32_16x16x32_bf16 v[50:53], v[114:117], v[162:165], v[50:53]
	v_mfma_f32_16x16x32_bf16 v[38:41], v[102:105], v[170:173], v[38:41]
	v_mfma_f32_16x16x32_bf16 v[34:37], v[114:117], v[170:173], v[34:37]
	v_mfma_f32_16x16x32_bf16 v[22:25], v[102:105], v[194:197], v[22:25]
	v_mfma_f32_16x16x32_bf16 v[18:21], v[114:117], v[194:197], v[18:21]
	v_mfma_f32_16x16x32_bf16 v[6:9], v[102:105], v[208:211], v[6:9]
	v_mfma_f32_16x16x32_bf16 v[2:5], v[114:117], v[208:211], v[2:5]
	v_mfma_f32_16x16x32_bf16 v[54:57], v[106:109], v[166:169], v[54:57]
	v_mfma_f32_16x16x32_bf16 v[50:53], v[118:121], v[166:169], v[50:53]
	v_mfma_f32_16x16x32_bf16 v[38:41], v[106:109], v[174:177], v[38:41]
	v_mfma_f32_16x16x32_bf16 v[34:37], v[118:121], v[174:177], v[34:37]
	v_mfma_f32_16x16x32_bf16 v[22:25], v[106:109], v[198:201], v[22:25]
	v_mfma_f32_16x16x32_bf16 v[18:21], v[118:121], v[198:201], v[18:21]
	v_mfma_f32_16x16x32_bf16 v[6:9], v[106:109], v[212:215], v[6:9]
	v_mfma_f32_16x16x32_bf16 v[2:5], v[118:121], v[212:215], v[2:5]
	s_setprio 0
	s_add_i32 s76, s76, 2
	s_add_u32 s62, s62, 0x100
	s_addc_u32 s63, s63, 0
	s_add_u32 s74, s74, 0x100
	s_addc_u32 s75, s75, 0
	s_cmp_gt_u32 s76, 29
	s_cbranch_scc0 .Lk2_Y

; #define PG8_STAGE(bufoff, gbase, voff) do { _Pragma("unroll") for (int _i = 0; _i < 2; ++_i) \
;         __builtin_amdgcn_global_load_lds((const unsigned*)((const char*)(gbase) + (voff)[_i]), (PG8_LAS unsigned*)(lds + (bufoff) + ldsw + _i * 8192), 16, 0, 0); } while (0)
; #define PG8_LDA(dst, b, h) do { _Pragma("unroll") for (int m = 0; m < 4; ++m) _Pragma("unroll") for (int k = 0; k < 2; ++k) dst[m][k] = *(const PG8_LAS bf16x8*)(lds + PG8_SA(b, h) + aoff + m * 2048 + k * 1024); } while (0)
; #define PG8_LDB(dst, b, h) do { _Pragma("unroll") for (int n = 0; n < 2; ++n) _Pragma("unroll") for (int k = 0; k < 2; ++k) dst[n][k] = *(const PG8_LAS bf16x8*)(lds + PG8_SB(b, h) + boff + n * 2048 + k * 1024); } while (0)
; #define PG8_WAIT_V(n) asm volatile("s_waitcnt vmcnt(" #n ")" ::: "memory")
; #define PG8_WAIT_L(n) asm volatile("s_waitcnt lgkmcnt(" #n ")" ::: "memory")
; #define PG8_BAR __builtin_amdgcn_s_barrier()
; #define PG8_SCHED __builtin_amdgcn_sched_barrier(0)
; template <class Epi, class Sched, bool ALIGN_EPI = false, bool SP2 = false, bool F8 = false>
; __device__ __forceinline__ void gemm_phase(PG8_LAS unsigned char* lds, const Gemm g, const Sched& S, const Epi& E) {
;     ...
;             const bool last = (t == nt - 2);
;             const char* a1 = cA + (size_t)(t + 1) * kstep;
;             const char* a2 = last ? nA : cA + (size_t)(t + 2) * kstep; const char* b2 = last ? nB : cB + (size_t)(t + 2) * kstep;
;             const char* a3 = a2 + kstep; const char* b3 = b2 + kstep;
;             if (last && has_next) S.a_ready(nxt);
;             if constexpr (SP2) {
;             PG8_LDB(B0, 0, 0); PG8_LDB(B1, 0, 1); PG8_SCHED; PG8_LDA(At, 0, 0); PG8_STAGE(PG8_SA(1, 1), a1 + hstepA, voffA);
;             PG8_WAIT_V(8); PG8_WAIT_L(0); PG8_BAR; PG8_MMA(0, 0, At, B0); PG8_MMA(0, 1, At, B1); PG8_BAR; PG8_SCHED;
.Lk3_Y:
	ds_read_b128 v[146:149], v175
	ds_read_b128 v[150:153], v175 offset:1024
	ds_read_b128 v[154:157], v175 offset:2048
	ds_read_b128 v[158:161], v175 offset:3072
	ds_read_b128 v[162:165], v176
	ds_read_b128 v[166:169], v176 offset:1024
	ds_read_b128 v[186:189], v176 offset:2048
	ds_read_b128 v[190:193], v176 offset:3072
	s_add_u32 s6, s56, 0x100
	s_addc_u32 s7, s57, 0
	s_cmp_eq_u32 s29, 28
	s_cselect_b32 s61, s53, s7
	s_cselect_b32 s60, s52, s6
	s_cselect_b32 s59, s15, s28
	s_cselect_b32 s58, s26, s27
	ds_read_b128 v[194:197], v177
	ds_read_b128 v[198:201], v177 offset:1024
	ds_read_b128 v[202:205], v177 offset:2048
	ds_read_b128 v[206:209], v177 offset:3072
	ds_read_b128 v[210:213], v177 offset:4096
	ds_read_b128 v[218:221], v177 offset:5120
	ds_read_b128 v[222:225], v177 offset:6144
	ds_read_b128 v[226:229], v177 offset:7168
	s_add_i32 m0, s65, 0xc000
	s_nop 0
	global_load_lds_dwordx4 v138, s[56:57]
	s_add_i32 m0, s65, 0xe000
	s_nop 0
	global_load_lds_dwordx4 v140, s[56:57]
	s_waitcnt vmcnt(8)
	s_waitcnt lgkmcnt(0)
	s_barrier
	s_setprio 3
	s_waitcnt lgkmcnt(0)
	v_mfma_f32_16x16x32_bf16 v[126:129], v[146:149], v[194:197], v[126:129]
	v_mfma_f32_16x16x32_bf16 v[122:125], v[154:157], v[194:197], v[122:125]
	v_mfma_f32_16x16x32_bf16 v[118:121], v[146:149], v[202:205], v[118:121]
	v_mfma_f32_16x16x32_bf16 v[114:117], v[154:157], v[202:205], v[114:117]
	v_mfma_f32_16x16x32_bf16 v[110:113], v[146:149], v[210:213], v[110:113]
	v_mfma_f32_16x16x32_bf16 v[102:105], v[154:157], v[210:213], v[102:105]
	v_mfma_f32_16x16x32_bf16 v[94:97], v[146:149], v[222:225], v[94:97]
	v_mfma_f32_16x16x32_bf16 v[86:89], v[154:157], v[222:225], v[86:89]
	v_mfma_f32_16x16x32_bf16 v[126:129], v[150:153], v[198:201], v[126:129]
	v_mfma_f32_16x16x32_bf16 v[122:125], v[158:161], v[198:201], v[122:125]
	v_mfma_f32_16x16x32_bf16 v[118:121], v[150:153], v[206:209], v[118:121]
	v_mfma_f32_16x16x32_bf16 v[114:117], v[158:161], v[206:209], v[114:117]
	v_mfma_f32_16x16x32_bf16 v[110:113], v[150:153], v[218:221], v[110:113]
	v_mfma_f32_16x16x32_bf16 v[102:105], v[158:161], v[218:221], v[102:105]
	v_mfma_f32_16x16x32_bf16 v[94:97], v[150:153], v[226:229], v[94:97]
	v_mfma_f32_16x16x32_bf16 v[86:89], v[158:161], v[226:229], v[86:89]


; #define PG8_STAGE(bufoff, gbase, voff) do { _Pragma("unroll") for (int _i = 0; _i < 2; ++_i) \
;         __builtin_amdgcn_global_load_lds((const unsigned*)((const char*)(gbase) + (voff)[_i]), (PG8_LAS unsigned*)(lds + (bufoff) + ldsw + _i * 8192), 16, 0, 0); } while (0)
; #define PG8_LDA(dst, b, h) do { _Pragma("unroll") for (int m = 0; m < 4; ++m) _Pragma("unroll") for (int k = 0; k < 2; ++k) dst[m][k] = *(const PG8_LAS bf16x8*)(lds + PG8_SA(b, h) + aoff + m * 2048 + k * 1024); } while (0)
; #define PG8_WAIT_V(n) asm volatile("s_waitcnt vmcnt(" #n ")" ::: "memory")
; #define PG8_WAIT_L(n) asm volatile("s_waitcnt lgkmcnt(" #n ")" ::: "memory")
; #define PG8_BAR __builtin_amdgcn_s_barrier()
; #define PG8_SCHED __builtin_amdgcn_sched_barrier(0)
; template <class Epi, class Sched, bool ALIGN_EPI = false, bool SP2 = false, bool F8 = false>
; __device__ __forceinline__ void gemm_phase(PG8_LAS unsigned char* lds, const Gemm g, const Sched& S, const Epi& E) {
;     ...
;             PG8_WAIT_V(8); PG8_WAIT_L(0); PG8_BAR; PG8_MMA(0, 0, At, B0); PG8_MMA(0, 1, At, B1); PG8_BAR; PG8_SCHED;
;             PG8_LDA(At, 0, 1); PG8_STAGE(PG8_SB(0, 0), b2, voffB); PG8_STAGE(PG8_SB(0, 1), b2 + hstep, voffB); PG8_STAGE(PG8_SA(0, 0), a2, voffA);
;             PG8_WAIT_V(8); PG8_WAIT_L(0); PG8_BAR; PG8_MMA(1, 0, At, B0); PG8_MMA(1, 1, At, B1); PG8_BAR; PG8_SCHED;
	v_mfma_f32_16x16x32_bf16 v[106:109], v[162:165], v[194:197], v[106:109]
	v_mfma_f32_16x16x32_bf16 v[98:101], v[186:189], v[194:197], v[98:101]
	v_mfma_f32_16x16x32_bf16 v[90:93], v[162:165], v[202:205], v[90:93]
	v_mfma_f32_16x16x32_bf16 v[82:85], v[186:189], v[202:205], v[82:85]
	v_mfma_f32_16x16x32_bf16 v[78:81], v[162:165], v[210:213], v[78:81]
	v_mfma_f32_16x16x32_bf16 v[74:77], v[186:189], v[210:213], v[74:77]
	v_mfma_f32_16x16x32_bf16 v[70:73], v[162:165], v[222:225], v[70:73]
	v_mfma_f32_16x16x32_bf16 v[66:69], v[186:189], v[222:225], v[66:69]
	v_mfma_f32_16x16x32_bf16 v[106:109], v[166:169], v[198:201], v[106:109]
	v_mfma_f32_16x16x32_bf16 v[98:101], v[190:193], v[198:201], v[98:101]
	v_mfma_f32_16x16x32_bf16 v[90:93], v[166:169], v[206:209], v[90:93]
	v_mfma_f32_16x16x32_bf16 v[82:85], v[190:193], v[206:209], v[82:85]
	v_mfma_f32_16x16x32_bf16 v[78:81], v[166:169], v[218:221], v[78:81]
	v_mfma_f32_16x16x32_bf16 v[74:77], v[190:193], v[218:221], v[74:77]
	v_mfma_f32_16x16x32_bf16 v[70:73], v[166:169], v[226:229], v[70:73]
	v_mfma_f32_16x16x32_bf16 v[66:69], v[190:193], v[226:229], v[66:69]
	s_setprio 0
	ds_read_b128 v[194:197], v177 offset:16384
	ds_read_b128 v[198:201], v177 offset:17408
	ds_read_b128 v[202:205], v177 offset:18432
	ds_read_b128 v[206:209], v177 offset:19456
	ds_read_b128 v[210:213], v177 offset:20480
	ds_read_b128 v[218:221], v177 offset:21504
	ds_read_b128 v[222:225], v177 offset:22528
	ds_read_b128 v[226:229], v177 offset:23552
	s_add_u32 s98, s58, 0x80000
	s_addc_u32 s99, s59, 0
	s_add_i32 s100, s75, s62
	s_add_i32 s101, s76, s62
	s_mov_b32 m0, s100
	s_nop 0
	global_load_lds_dwordx4 v134, s[58:59]
	s_add_i32 m0, s100, 0x2000
	s_nop 0
	global_load_lds_dwordx4 v130, s[58:59]
	s_mov_b32 m0, s101
	s_nop 0
	global_load_lds_dwordx4 v134, s[98:99]
	s_add_i32 m0, s101, 0x2000
	s_nop 0
	global_load_lds_dwordx4 v130, s[98:99]
	s_mov_b32 m0, s65
	s_nop 0
	global_load_lds_dwordx4 v136, s[60:61]
	s_mov_b32 m0, s66
	s_nop 0
	global_load_lds_dwordx4 v132, s[60:61]
	s_waitcnt vmcnt(8)
	s_waitcnt lgkmcnt(0)
	s_barrier
	s_setprio 3
	s_waitcnt lgkmcnt(0)
	v_mfma_f32_16x16x32_bf16 v[62:65], v[146:149], v[194:197], v[62:65]
	v_mfma_f32_16x16x32_bf16 v[58:61], v[154:157], v[194:197], v[58:61]
	v_mfma_f32_16x16x32_bf16 v[54:57], v[146:149], v[202:205], v[54:57]
	v_mfma_f32_16x16x32_bf16 v[50:53], v[154:157], v[202:205], v[50:53]
	v_mfma_f32_16x16x32_bf16 v[38:41], v[146:149], v[210:213], v[38:41]
	v_mfma_f32_16x16x32_bf16 v[34:37], v[154:157], v[210:213], v[34:37]
	v_mfma_f32_16x16x32_bf16 v[22:25], v[146:149], v[222:225], v[22:25]
	v_mfma_f32_16x16x32_bf16 v[18:21], v[154:157], v[222:225], v[18:21]
	v_mfma_f32_16x16x32_bf16 v[62:65], v[150:153], v[198:201], v[62:65]
	v_mfma_f32_16x16x32_bf16 v[58:61], v[158:161], v[198:201], v[58:61]
	v_mfma_f32_16x16x32_bf16 v[54:57], v[150:153], v[206:209], v[54:57]
	v_mfma_f32_16x16x32_bf16 v[50:53], v[158:161], v[206:209], v[50:53]
	v_mfma_f32_16x16x32_bf16 v[38:41], v[150:153], v[218:221], v[38:41]
	v_mfma_f32_16x16x32_bf16 v[34:37], v[158:161], v[218:221], v[34:37]
	v_mfma_f32_16x16x32_bf16 v[22:25], v[150:153], v[226:229], v[22:25]
	v_mfma_f32_16x16x32_bf16 v[18:21], v[158:161], v[226:229], v[18:21]


; #define PG8_STAGE(bufoff, gbase, voff) do { _Pragma("unroll") for (int _i = 0; _i < 2; ++_i) \
;         __builtin_amdgcn_global_load_lds((const unsigned*)((const char*)(gbase) + (voff)[_i]), (PG8_LAS unsigned*)(lds + (bufoff) + ldsw + _i * 8192), 16, 0, 0); } while (0)
; #define PG8_LDA(dst, b, h) do { _Pragma("unroll") for (int m = 0; m < 4; ++m) _Pragma("unroll") for (int k = 0; k < 2; ++k) dst[m][k] = *(const PG8_LAS bf16x8*)(lds + PG8_SA(b, h) + aoff + m * 2048 + k * 1024); } while (0)
; #define PG8_LDB(dst, b, h) do { _Pragma("unroll") for (int n = 0; n < 2; ++n) _Pragma("unroll") for (int k = 0; k < 2; ++k) dst[n][k] = *(const PG8_LAS bf16x8*)(lds + PG8_SB(b, h) + boff + n * 2048 + k * 1024); } while (0)
; #define PG8_WAIT_V(n) asm volatile("s_waitcnt vmcnt(" #n ")" ::: "memory")
; #define PG8_WAIT_L(n) asm volatile("s_waitcnt lgkmcnt(" #n ")" ::: "memory")
; #define PG8_BAR __builtin_amdgcn_s_barrier()
; #define PG8_SCHED __builtin_amdgcn_sched_barrier(0)
; template <class Epi, class Sched, bool ALIGN_EPI = false, bool SP2 = false, bool F8 = false>
; __device__ __forceinline__ void gemm_phase(PG8_LAS unsigned char* lds, const Gemm g, const Sched& S, const Epi& E) {
;     ...
;             PG8_WAIT_V(8); PG8_WAIT_L(0); PG8_BAR; PG8_MMA(1, 0, At, B0); PG8_MMA(1, 1, At, B1); PG8_BAR; PG8_SCHED;
;             PG8_LDB(B0, 1, 0); PG8_LDB(B1, 1, 1); PG8_SCHED; PG8_LDA(At, 1, 0); PG8_STAGE(PG8_SA(0, 1), a2 + hstepA, voffA);
;             PG8_WAIT_V(8); PG8_WAIT_L(0); PG8_BAR; PG8_MMA(0, 0, At, B0); PG8_MMA(0, 1, At, B1); PG8_BAR; PG8_SCHED;
	v_mfma_f32_16x16x32_bf16 v[46:49], v[162:165], v[194:197], v[46:49]
	v_mfma_f32_16x16x32_bf16 v[42:45], v[186:189], v[194:197], v[42:45]
	v_mfma_f32_16x16x32_bf16 v[30:33], v[162:165], v[202:205], v[30:33]
	v_mfma_f32_16x16x32_bf16 v[26:29], v[186:189], v[202:205], v[26:29]
	v_mfma_f32_16x16x32_bf16 v[14:17], v[162:165], v[210:213], v[14:17]
	v_mfma_f32_16x16x32_bf16 v[10:13], v[186:189], v[210:213], v[10:13]
	v_mfma_f32_16x16x32_bf16 v[6:9], v[162:165], v[222:225], v[6:9]
	v_mfma_f32_16x16x32_bf16 v[2:5], v[186:189], v[222:225], v[2:5]
	v_mfma_f32_16x16x32_bf16 v[46:49], v[166:169], v[198:201], v[46:49]
	v_mfma_f32_16x16x32_bf16 v[42:45], v[190:193], v[198:201], v[42:45]
	v_mfma_f32_16x16x32_bf16 v[30:33], v[166:169], v[206:209], v[30:33]
	v_mfma_f32_16x16x32_bf16 v[26:29], v[190:193], v[206:209], v[26:29]
	v_mfma_f32_16x16x32_bf16 v[14:17], v[166:169], v[218:221], v[14:17]
	v_mfma_f32_16x16x32_bf16 v[10:13], v[190:193], v[218:221], v[10:13]
	v_mfma_f32_16x16x32_bf16 v[6:9], v[166:169], v[226:229], v[6:9]
	v_mfma_f32_16x16x32_bf16 v[2:5], v[190:193], v[226:229], v[2:5]
	s_setprio 0
	s_add_i32 s33, 0, 0x18000
	s_add_i32 s36, 0, 0x1c000
	v_add_u32_e32 v158, s33, v174
	v_add_u32_e32 v185, s36, v174
	ds_read_b128 v[146:149], v158
	ds_read_b128 v[150:153], v158 offset:1024
	ds_read_b128 v[154:157], v158 offset:2048
	ds_read_b128 v[158:161], v158 offset:3072
	ds_read_b128 v[162:165], v185
	ds_read_b128 v[166:169], v185 offset:1024
	ds_read_b128 v[186:189], v185 offset:2048
	ds_read_b128 v[190:193], v185 offset:3072
	ds_read_b128 v[194:197], v177 offset:32768
	ds_read_b128 v[198:201], v177 offset:33792
	ds_read_b128 v[202:205], v177 offset:34816
	ds_read_b128 v[206:209], v177 offset:35840
	ds_read_b128 v[210:213], v177 offset:36864
	ds_read_b128 v[218:221], v177 offset:37888
	ds_read_b128 v[222:225], v177 offset:38912
	ds_read_b128 v[226:229], v177 offset:39936
	s_add_u32 s98, s60, 0x100000
	s_addc_u32 s99, s61, 0
	s_mov_b32 m0, s67
	s_nop 0
	global_load_lds_dwordx4 v136, s[98:99]
	s_mov_b32 m0, s68
	s_nop 0
	global_load_lds_dwordx4 v132, s[98:99]
	s_waitcnt vmcnt(8)
	s_waitcnt lgkmcnt(0)
	s_barrier
	s_setprio 3
	s_waitcnt lgkmcnt(0)
	v_mfma_f32_16x16x32_bf16 v[126:129], v[146:149], v[194:197], v[126:129]
	v_mfma_f32_16x16x32_bf16 v[122:125], v[154:157], v[194:197], v[122:125]
	v_mfma_f32_16x16x32_bf16 v[118:121], v[146:149], v[202:205], v[118:121]
	v_mfma_f32_16x16x32_bf16 v[114:117], v[154:157], v[202:205], v[114:117]
	v_mfma_f32_16x16x32_bf16 v[110:113], v[146:149], v[210:213], v[110:113]
	v_mfma_f32_16x16x32_bf16 v[102:105], v[154:157], v[210:213], v[102:105]
	v_mfma_f32_16x16x32_bf16 v[94:97], v[146:149], v[222:225], v[94:97]
	v_mfma_f32_16x16x32_bf16 v[86:89], v[154:157], v[222:225], v[86:89]
	v_mfma_f32_16x16x32_bf16 v[126:129], v[150:153], v[198:201], v[126:129]
	v_mfma_f32_16x16x32_bf16 v[122:125], v[158:161], v[198:201], v[122:125]
	v_mfma_f32_16x16x32_bf16 v[118:121], v[150:153], v[206:209], v[118:121]
	v_mfma_f32_16x16x32_bf16 v[114:117], v[158:161], v[206:209], v[114:117]
	v_mfma_f32_16x16x32_bf16 v[110:113], v[150:153], v[218:221], v[110:113]
	v_mfma_f32_16x16x32_bf16 v[102:105], v[158:161], v[218:221], v[102:105]
	v_mfma_f32_16x16x32_bf16 v[94:97], v[150:153], v[226:229], v[94:97]
	v_mfma_f32_16x16x32_bf16 v[86:89], v[158:161], v[226:229], v[86:89]


; #define PG8_STAGE(bufoff, gbase, voff) do { _Pragma("unroll") for (int _i = 0; _i < 2; ++_i) \
;         __builtin_amdgcn_global_load_lds((const unsigned*)((const char*)(gbase) + (voff)[_i]), (PG8_LAS unsigned*)(lds + (bufoff) + ldsw + _i * 8192), 16, 0, 0); } while (0)
; #define PG8_LDA(dst, b, h) do { _Pragma("unroll") for (int m = 0; m < 4; ++m) _Pragma("unroll") for (int k = 0; k < 2; ++k) dst[m][k] = *(const PG8_LAS bf16x8*)(lds + PG8_SA(b, h) + aoff + m * 2048 + k * 1024); } while (0)
; #define PG8_WAIT_V(n) asm volatile("s_waitcnt vmcnt(" #n ")" ::: "memory")
; #define PG8_WAIT_L(n) asm volatile("s_waitcnt lgkmcnt(" #n ")" ::: "memory")
; #define PG8_BAR __builtin_amdgcn_s_barrier()
; #define PG8_SCHED __builtin_amdgcn_sched_barrier(0)
; template <class Epi, class Sched, bool ALIGN_EPI = false, bool SP2 = false, bool F8 = false>
; __device__ __forceinline__ void gemm_phase(PG8_LAS unsigned char* lds, const Gemm g, const Sched& S, const Epi& E) {
;     ...
;             PG8_WAIT_V(8); PG8_WAIT_L(0); PG8_BAR; PG8_MMA(0, 0, At, B0); PG8_MMA(0, 1, At, B1); PG8_BAR; PG8_SCHED;
;             PG8_LDA(At, 1, 1); PG8_STAGE(PG8_SB(1, 0), b3, voffB); PG8_STAGE(PG8_SB(1, 1), b3 + hstep, voffB); PG8_STAGE(PG8_SA(1, 0), a3, voffA);
;             PG8_WAIT_V(8); PG8_WAIT_L(0); PG8_BAR; PG8_MMA(1, 0, At, B0); PG8_MMA(1, 1, At, B1); PG8_BAR; PG8_SCHED;
	v_mfma_f32_16x16x32_bf16 v[106:109], v[162:165], v[194:197], v[106:109]
	v_mfma_f32_16x16x32_bf16 v[98:101], v[186:189], v[194:197], v[98:101]
	v_mfma_f32_16x16x32_bf16 v[90:93], v[162:165], v[202:205], v[90:93]
	v_mfma_f32_16x16x32_bf16 v[82:85], v[186:189], v[202:205], v[82:85]
	v_mfma_f32_16x16x32_bf16 v[78:81], v[162:165], v[210:213], v[78:81]
	v_mfma_f32_16x16x32_bf16 v[74:77], v[186:189], v[210:213], v[74:77]
	v_mfma_f32_16x16x32_bf16 v[70:73], v[162:165], v[222:225], v[70:73]
	v_mfma_f32_16x16x32_bf16 v[66:69], v[186:189], v[222:225], v[66:69]
	v_mfma_f32_16x16x32_bf16 v[106:109], v[166:169], v[198:201], v[106:109]
	v_mfma_f32_16x16x32_bf16 v[98:101], v[190:193], v[198:201], v[98:101]
	v_mfma_f32_16x16x32_bf16 v[90:93], v[166:169], v[206:209], v[90:93]
	v_mfma_f32_16x16x32_bf16 v[82:85], v[190:193], v[206:209], v[82:85]
	v_mfma_f32_16x16x32_bf16 v[78:81], v[166:169], v[218:221], v[78:81]
	v_mfma_f32_16x16x32_bf16 v[74:77], v[190:193], v[218:221], v[74:77]
	v_mfma_f32_16x16x32_bf16 v[70:73], v[166:169], v[226:229], v[70:73]
	v_mfma_f32_16x16x32_bf16 v[66:69], v[190:193], v[226:229], v[66:69]
	s_setprio 0
	ds_read_b128 v[194:197], v177 offset:49152
	ds_read_b128 v[198:201], v177 offset:50176
	ds_read_b128 v[202:205], v177 offset:51200
	ds_read_b128 v[206:209], v177 offset:52224
	ds_read_b128 v[210:213], v177 offset:53248
	ds_read_b128 v[218:221], v177 offset:54272
	ds_read_b128 v[222:225], v177 offset:55296
	ds_read_b128 v[226:229], v177 offset:56320
	s_add_u32 s98, s58, 0x80
	s_addc_u32 s99, s59, 0
	s_add_u32 s100, s58, 0x80080
	s_addc_u32 s101, s59, 0
	s_add_u32 s24, s60, 0x80
	s_addc_u32 s25, s61, 0
	s_add_i32 m0, s62, 0x18000
	s_nop 0
	global_load_lds_dwordx4 v134, s[98:99]
	s_add_i32 m0, s62, 0x1a000
	s_nop 0
	global_load_lds_dwordx4 v130, s[98:99]
	s_add_i32 m0, s62, 0x1c000
	s_nop 0
	global_load_lds_dwordx4 v134, s[100:101]
	s_add_i32 m0, s62, 0x1e000
	s_nop 0
	global_load_lds_dwordx4 v130, s[100:101]
	s_mov_b32 m0, s71
	s_nop 0
	global_load_lds_dwordx4 v136, s[24:25]
	s_mov_b32 m0, s72
	s_nop 0
	global_load_lds_dwordx4 v132, s[24:25]
	s_waitcnt vmcnt(8)
	s_waitcnt lgkmcnt(0)
	s_barrier
	s_setprio 3
	s_waitcnt lgkmcnt(0)
	v_mfma_f32_16x16x32_bf16 v[62:65], v[146:149], v[194:197], v[62:65]
	v_mfma_f32_16x16x32_bf16 v[58:61], v[154:157], v[194:197], v[58:61]
	v_mfma_f32_16x16x32_bf16 v[54:57], v[146:149], v[202:205], v[54:57]
	v_mfma_f32_16x16x32_bf16 v[50:53], v[154:157], v[202:205], v[50:53]
	v_mfma_f32_16x16x32_bf16 v[38:41], v[146:149], v[210:213], v[38:41]
	v_mfma_f32_16x16x32_bf16 v[34:37], v[154:157], v[210:213], v[34:37]
	v_mfma_f32_16x16x32_bf16 v[22:25], v[146:149], v[222:225], v[22:25]
	v_mfma_f32_16x16x32_bf16 v[18:21], v[154:157], v[222:225], v[18:21]
	v_mfma_f32_16x16x32_bf16 v[62:65], v[150:153], v[198:201], v[62:65]
	v_mfma_f32_16x16x32_bf16 v[58:61], v[158:161], v[198:201], v[58:61]
	v_mfma_f32_16x16x32_bf16 v[54:57], v[150:153], v[206:209], v[54:57]
	v_mfma_f32_16x16x32_bf16 v[50:53], v[158:161], v[206:209], v[50:53]
	v_mfma_f32_16x16x32_bf16 v[38:41], v[150:153], v[218:221], v[38:41]
	v_mfma_f32_16x16x32_bf16 v[34:37], v[158:161], v[218:221], v[34:37]
	v_mfma_f32_16x16x32_bf16 v[22:25], v[150:153], v[226:229], v[22:25]
	v_mfma_f32_16x16x32_bf16 v[18:21], v[158:161], v[226:229], v[18:21]


; #define PG8_WAIT_V(n) asm volatile("s_waitcnt vmcnt(" #n ")" ::: "memory")
; #define PG8_WAIT_L(n) asm volatile("s_waitcnt lgkmcnt(" #n ")" ::: "memory")
; #define PG8_BAR __builtin_amdgcn_s_barrier()
; #define PG8_SCHED __builtin_amdgcn_sched_barrier(0)
; template <class Epi, class Sched, bool ALIGN_EPI = false, bool SP2 = false, bool F8 = false>
; __device__ __forceinline__ void gemm_phase(PG8_LAS unsigned char* lds, const Gemm g, const Sched& S, const Epi& E) {
;     ...
;         for (int t = 0; t < nt; t += 2) {
;     ...
;             PG8_WAIT_V(8); PG8_WAIT_L(0); PG8_BAR; PG8_MMA(1, 0, At, B0); PG8_MMA(1, 1, At, B1); PG8_BAR; PG8_SCHED;
	v_mfma_f32_16x16x32_bf16 v[46:49], v[162:165], v[194:197], v[46:49]
	v_mfma_f32_16x16x32_bf16 v[42:45], v[186:189], v[194:197], v[42:45]
	v_mfma_f32_16x16x32_bf16 v[30:33], v[162:165], v[202:205], v[30:33]
	v_mfma_f32_16x16x32_bf16 v[26:29], v[186:189], v[202:205], v[26:29]
	v_mfma_f32_16x16x32_bf16 v[14:17], v[162:165], v[210:213], v[14:17]
	v_mfma_f32_16x16x32_bf16 v[10:13], v[186:189], v[210:213], v[10:13]
	v_mfma_f32_16x16x32_bf16 v[6:9], v[162:165], v[222:225], v[6:9]
	v_mfma_f32_16x16x32_bf16 v[2:5], v[186:189], v[222:225], v[2:5]
	v_mfma_f32_16x16x32_bf16 v[46:49], v[166:169], v[198:201], v[46:49]
	v_mfma_f32_16x16x32_bf16 v[42:45], v[190:193], v[198:201], v[42:45]
	v_mfma_f32_16x16x32_bf16 v[30:33], v[166:169], v[206:209], v[30:33]
	v_mfma_f32_16x16x32_bf16 v[26:29], v[190:193], v[206:209], v[26:29]
	v_mfma_f32_16x16x32_bf16 v[14:17], v[166:169], v[218:221], v[14:17]
	v_mfma_f32_16x16x32_bf16 v[10:13], v[190:193], v[218:221], v[10:13]
	v_mfma_f32_16x16x32_bf16 v[6:9], v[166:169], v[226:229], v[6:9]
	v_mfma_f32_16x16x32_bf16 v[2:5], v[190:193], v[226:229], v[2:5]
	s_setprio 0
	s_add_i32 s29, s29, 2
	s_add_u32 s27, s27, 0x100
	s_addc_u32 s28, s28, 0
	s_cmp_gt_u32 s29, 29
	s_mov_b64 s[56:57], s[6:7]
	s_cbranch_scc0 .Lk3_Y

; #define PG8_STAGE(bufoff, gbase, voff) do { _Pragma("unroll") for (int _i = 0; _i < 2; ++_i) \
;         __builtin_amdgcn_global_load_lds((const unsigned*)((const char*)(gbase) + (voff)[_i]), (PG8_LAS unsigned*)(lds + (bufoff) + ldsw + _i * 8192), 16, 0, 0); } while (0)
; #define PG8_LDA(dst, b, h) do { _Pragma("unroll") for (int m = 0; m < 4; ++m) _Pragma("unroll") for (int k = 0; k < 2; ++k) dst[m][k] = *(const PG8_LAS bf16x8*)(lds + PG8_SA(b, h) + aoff + m * 2048 + k * 1024); } while (0)
; #define PG8_LDB(dst, b, h) do { _Pragma("unroll") for (int n = 0; n < 2; ++n) _Pragma("unroll") for (int k = 0; k < 2; ++k) dst[n][k] = *(const PG8_LAS bf16x8*)(lds + PG8_SB(b, h) + boff + n * 2048 + k * 1024); } while (0)
; #define PG8_WAIT_V(n) asm volatile("s_waitcnt vmcnt(" #n ")" ::: "memory")
; #define PG8_WAIT_L(n) asm volatile("s_waitcnt lgkmcnt(" #n ")" ::: "memory")
; #define PG8_BAR __builtin_amdgcn_s_barrier()
; #define PG8_SCHED __builtin_amdgcn_sched_barrier(0)
; template <class Epi, class Sched, bool ALIGN_EPI = false, bool SP2 = false, bool F8 = false>
; __device__ __forceinline__ void gemm_phase(PG8_LAS unsigned char* lds, const Gemm g, const Sched& S, const Epi& E) {
;     ...
;             const bool last = (t == nt - 2);
;             const char* a1 = cA + (size_t)(t + 1) * kstep;
;             const char* a2 = last ? nA : cA + (size_t)(t + 2) * kstep; const char* b2 = last ? nB : cB + (size_t)(t + 2) * kstep;
;             const char* a3 = a2 + kstep; const char* b3 = b2 + kstep;
;             if (last && has_next) S.a_ready(nxt);
;             if constexpr (SP2) {
;             PG8_LDB(B0, 0, 0); PG8_LDB(B1, 0, 1); PG8_SCHED; PG8_LDA(At, 0, 0); PG8_STAGE(PG8_SA(1, 1), a1 + hstepA, voffA);
;             PG8_WAIT_V(8); PG8_WAIT_L(0); PG8_BAR; PG8_MMA(0, 0, At, B0); PG8_MMA(0, 1, At, B1); PG8_BAR; PG8_SCHED;
.Lk4_Y:
	ds_read_b128 v[24:27], v197
	ds_read_b128 v[28:31], v197 offset:1024
	ds_read_b128 v[16:19], v197 offset:2048
	ds_read_b128 v[20:23], v197 offset:3072
	ds_read_b128 v[8:11], v198
	ds_read_b128 v[12:15], v198 offset:1024
	ds_read_b128 v[0:3], v198 offset:2048
	ds_read_b128 v[4:7], v198 offset:3072
	s_add_u32 s24, s52, 0xfff50080
	s_addc_u32 s25, s53, -1
	s_cmp_eq_u32 s67, 40
	s_cselect_b32 s57, s7, s25
	s_cselect_b32 s56, s6, s24
	s_cselect_b32 s55, s51, s66
	s_cselect_b32 s54, s50, s65
	s_add_i32 m0, s15, 0xc000
	ds_read_b128 v[176:179], v199
	ds_read_b128 v[180:183], v199 offset:1024
	ds_read_b128 v[184:187], v199 offset:2048
	ds_read_b128 v[188:191], v199 offset:3072
	ds_read_b128 v[200:203], v199 offset:4096
	ds_read_b128 v[204:207], v199 offset:5120
	ds_read_b128 v[208:211], v199 offset:6144
	ds_read_b128 v[212:215], v199 offset:7168
	global_load_lds_dwordx4 v168, s[52:53]
	s_add_i32 m0, s15, 0xe000
	s_nop 0
	global_load_lds_dwordx4 v170, s[52:53]
	s_waitcnt vmcnt(8)
	s_waitcnt lgkmcnt(0)
	s_barrier
	s_setprio 3
	s_waitcnt lgkmcnt(0)
	v_mfma_f32_16x16x128_f8f6f4 v[156:159], v[24:31], v[176:183], v[156:159]
	v_mfma_f32_16x16x128_f8f6f4 v[152:155], v[16:23], v[176:183], v[152:155]
	v_mfma_f32_16x16x128_f8f6f4 v[140:143], v[24:31], v[184:191], v[140:143]
	v_mfma_f32_16x16x128_f8f6f4 v[136:139], v[16:23], v[184:191], v[136:139]
	v_mfma_f32_16x16x128_f8f6f4 v[124:127], v[24:31], v[200:207], v[124:127]
	v_mfma_f32_16x16x128_f8f6f4 v[120:123], v[16:23], v[200:207], v[120:123]
	v_mfma_f32_16x16x128_f8f6f4 v[108:111], v[24:31], v[208:215], v[108:111]
	v_mfma_f32_16x16x128_f8f6f4 v[104:107], v[16:23], v[208:215], v[104:107]


; #define PG8_STAGE(bufoff, gbase, voff) do { _Pragma("unroll") for (int _i = 0; _i < 2; ++_i) \
;         __builtin_amdgcn_global_load_lds((const unsigned*)((const char*)(gbase) + (voff)[_i]), (PG8_LAS unsigned*)(lds + (bufoff) + ldsw + _i * 8192), 16, 0, 0); } while (0)
; #define PG8_LDA(dst, b, h) do { _Pragma("unroll") for (int m = 0; m < 4; ++m) _Pragma("unroll") for (int k = 0; k < 2; ++k) dst[m][k] = *(const PG8_LAS bf16x8*)(lds + PG8_SA(b, h) + aoff + m * 2048 + k * 1024); } while (0)
; #define PG8_WAIT_V(n) asm volatile("s_waitcnt vmcnt(" #n ")" ::: "memory")
; #define PG8_WAIT_L(n) asm volatile("s_waitcnt lgkmcnt(" #n ")" ::: "memory")
; #define PG8_BAR __builtin_amdgcn_s_barrier()
; #define PG8_SCHED __builtin_amdgcn_sched_barrier(0)
; template <class Epi, class Sched, bool ALIGN_EPI = false, bool SP2 = false, bool F8 = false>
; __device__ __forceinline__ void gemm_phase(PG8_LAS unsigned char* lds, const Gemm g, const Sched& S, const Epi& E) {
;     ...
;             PG8_WAIT_V(8); PG8_WAIT_L(0); PG8_BAR; PG8_MMA(0, 0, At, B0); PG8_MMA(0, 1, At, B1); PG8_BAR; PG8_SCHED;
;             PG8_LDA(At, 0, 1); PG8_STAGE(PG8_SB(0, 0), b2, voffB); PG8_STAGE(PG8_SB(0, 1), b2 + hstep, voffB); PG8_STAGE(PG8_SA(0, 0), a2, voffA);
;             PG8_WAIT_V(8); PG8_WAIT_L(0); PG8_BAR; PG8_MMA(1, 0, At, B0); PG8_MMA(1, 1, At, B1); PG8_BAR; PG8_SCHED;
	v_mfma_f32_16x16x128_f8f6f4 v[148:151], v[8:15], v[176:183], v[148:151]
	v_mfma_f32_16x16x128_f8f6f4 v[144:147], v[0:7], v[176:183], v[144:147]
	v_mfma_f32_16x16x128_f8f6f4 v[132:135], v[8:15], v[184:191], v[132:135]
	v_mfma_f32_16x16x128_f8f6f4 v[128:131], v[0:7], v[184:191], v[128:131]
	v_mfma_f32_16x16x128_f8f6f4 v[116:119], v[8:15], v[200:207], v[116:119]
	v_mfma_f32_16x16x128_f8f6f4 v[112:115], v[0:7], v[200:207], v[112:115]
	v_mfma_f32_16x16x128_f8f6f4 v[100:103], v[8:15], v[208:215], v[100:103]
	v_mfma_f32_16x16x128_f8f6f4 v[96:99], v[0:7], v[208:215], v[96:99]
	s_setprio 0
	s_add_i32 s24, s59, s14
	s_mov_b32 m0, s24
	ds_read_b128 v[184:187], v199 offset:16384
	ds_read_b128 v[188:191], v199 offset:17408
	ds_read_b128 v[200:203], v199 offset:18432
	ds_read_b128 v[204:207], v199 offset:19456
	ds_read_b128 v[208:211], v199 offset:20480
	ds_read_b128 v[212:215], v199 offset:21504
	ds_read_b128 v[218:221], v199 offset:22528
	ds_read_b128 v[222:225], v199 offset:23552
	global_load_lds_dwordx4 v162, s[54:55]
	s_add_i32 m0, s24, 0x2000
	s_add_u32 s24, s54, 0xb0000
	s_addc_u32 s25, s55, 0
	s_add_i32 s36, s60, s14
	global_load_lds_dwordx4 v166, s[54:55]
	s_mov_b32 m0, s36
	s_nop 0
	global_load_lds_dwordx4 v162, s[24:25]
	s_add_i32 m0, s36, 0x2000
	s_nop 0
	global_load_lds_dwordx4 v166, s[24:25]
	s_mov_b32 m0, s15
	s_nop 0
	global_load_lds_dwordx4 v160, s[56:57]
	s_mov_b32 m0, s21
	s_nop 0
	global_load_lds_dwordx4 v164, s[56:57]
	s_waitcnt vmcnt(8)
	s_waitcnt lgkmcnt(0)
	s_barrier
	s_setprio 3
	s_waitcnt lgkmcnt(0)
	v_mfma_f32_16x16x128_f8f6f4 v[92:95], v[24:31], v[184:191], v[92:95]
	v_mfma_f32_16x16x128_f8f6f4 v[88:91], v[16:23], v[184:191], v[88:91]
	v_mfma_f32_16x16x128_f8f6f4 v[76:79], v[24:31], v[200:207], v[76:79]
	v_mfma_f32_16x16x128_f8f6f4 v[72:75], v[16:23], v[200:207], v[72:75]
	v_mfma_f32_16x16x128_f8f6f4 v[60:63], v[24:31], v[208:215], v[60:63]
	v_mfma_f32_16x16x128_f8f6f4 v[56:59], v[16:23], v[208:215], v[56:59]
	v_mfma_f32_16x16x128_f8f6f4 v[44:47], v[24:31], v[218:225], v[44:47]
	v_mfma_f32_16x16x128_f8f6f4 v[40:43], v[16:23], v[218:225], v[40:43]


; #define PG8_STAGE(bufoff, gbase, voff) do { _Pragma("unroll") for (int _i = 0; _i < 2; ++_i) \
;         __builtin_amdgcn_global_load_lds((const unsigned*)((const char*)(gbase) + (voff)[_i]), (PG8_LAS unsigned*)(lds + (bufoff) + ldsw + _i * 8192), 16, 0, 0); } while (0)
; #define PG8_LDA(dst, b, h) do { _Pragma("unroll") for (int m = 0; m < 4; ++m) _Pragma("unroll") for (int k = 0; k < 2; ++k) dst[m][k] = *(const PG8_LAS bf16x8*)(lds + PG8_SA(b, h) + aoff + m * 2048 + k * 1024); } while (0)
; #define PG8_LDB(dst, b, h) do { _Pragma("unroll") for (int n = 0; n < 2; ++n) _Pragma("unroll") for (int k = 0; k < 2; ++k) dst[n][k] = *(const PG8_LAS bf16x8*)(lds + PG8_SB(b, h) + boff + n * 2048 + k * 1024); } while (0)
; #define PG8_WAIT_V(n) asm volatile("s_waitcnt vmcnt(" #n ")" ::: "memory")
; #define PG8_WAIT_L(n) asm volatile("s_waitcnt lgkmcnt(" #n ")" ::: "memory")
; #define PG8_BAR __builtin_amdgcn_s_barrier()
; #define PG8_SCHED __builtin_amdgcn_sched_barrier(0)
; template <class Epi, class Sched, bool ALIGN_EPI = false, bool SP2 = false, bool F8 = false>
; __device__ __forceinline__ void gemm_phase(PG8_LAS unsigned char* lds, const Gemm g, const Sched& S, const Epi& E) {
;     ...
;             PG8_WAIT_V(8); PG8_WAIT_L(0); PG8_BAR; PG8_MMA(1, 0, At, B0); PG8_MMA(1, 1, At, B1); PG8_BAR; PG8_SCHED;
;             PG8_LDB(B0, 1, 0); PG8_LDB(B1, 1, 1); PG8_SCHED; PG8_LDA(At, 1, 0); PG8_STAGE(PG8_SA(0, 1), a2 + hstepA, voffA);
;             PG8_WAIT_V(8); PG8_WAIT_L(0); PG8_BAR; PG8_MMA(0, 0, At, B0); PG8_MMA(0, 1, At, B1); PG8_BAR; PG8_SCHED;
	v_mfma_f32_16x16x128_f8f6f4 v[84:87], v[8:15], v[184:191], v[84:87]
	v_mfma_f32_16x16x128_f8f6f4 v[80:83], v[0:7], v[184:191], v[80:83]
	v_mfma_f32_16x16x128_f8f6f4 v[68:71], v[8:15], v[200:207], v[68:71]
	v_mfma_f32_16x16x128_f8f6f4 v[64:67], v[0:7], v[200:207], v[64:67]
	v_mfma_f32_16x16x128_f8f6f4 v[52:55], v[8:15], v[208:215], v[52:55]
	v_mfma_f32_16x16x128_f8f6f4 v[48:51], v[0:7], v[208:215], v[48:51]
	v_mfma_f32_16x16x128_f8f6f4 v[36:39], v[8:15], v[218:225], v[36:39]
	v_mfma_f32_16x16x128_f8f6f4 v[32:35], v[0:7], v[218:225], v[32:35]
	s_setprio 0
	s_add_i32 s36, 0, 0x18000
	s_add_i32 s37, 0, 0x1c000
	v_add_u32_e32 v12, s36, v195
	v_add_u32_e32 v28, s37, v195
	ds_read_b128 v[0:3], v12
	ds_read_b128 v[4:7], v12 offset:1024
	ds_read_b128 v[8:11], v12 offset:2048
	ds_read_b128 v[12:15], v12 offset:3072
	ds_read_b128 v[16:19], v28
	ds_read_b128 v[20:23], v28 offset:1024
	ds_read_b128 v[24:27], v28 offset:2048
	ds_read_b128 v[28:31], v28 offset:3072
	s_add_u32 s24, s56, 0xb0000
	s_addc_u32 s25, s57, 0
	s_mov_b32 m0, s23
	ds_read_b128 v[184:187], v199 offset:32768
	ds_read_b128 v[188:191], v199 offset:33792
	ds_read_b128 v[200:203], v199 offset:34816
	ds_read_b128 v[204:207], v199 offset:35840
	ds_read_b128 v[208:211], v199 offset:36864
	ds_read_b128 v[212:215], v199 offset:37888
	ds_read_b128 v[218:221], v199 offset:38912
	ds_read_b128 v[222:225], v199 offset:39936
	global_load_lds_dwordx4 v160, s[24:25]
	s_mov_b32 m0, s26
	s_nop 0
	global_load_lds_dwordx4 v164, s[24:25]
	s_waitcnt vmcnt(8)
	s_waitcnt lgkmcnt(0)
	s_barrier
	s_setprio 3
	s_waitcnt lgkmcnt(0)
	v_mfma_f32_16x16x128_f8f6f4 v[156:159], v[0:7], v[184:191], v[156:159]
	v_mfma_f32_16x16x128_f8f6f4 v[152:155], v[8:15], v[184:191], v[152:155]
	v_mfma_f32_16x16x128_f8f6f4 v[140:143], v[0:7], v[200:207], v[140:143]
	v_mfma_f32_16x16x128_f8f6f4 v[136:139], v[8:15], v[200:207], v[136:139]
	v_mfma_f32_16x16x128_f8f6f4 v[124:127], v[0:7], v[208:215], v[124:127]
	v_mfma_f32_16x16x128_f8f6f4 v[120:123], v[8:15], v[208:215], v[120:123]
	v_mfma_f32_16x16x128_f8f6f4 v[108:111], v[0:7], v[218:225], v[108:111]
	v_mfma_f32_16x16x128_f8f6f4 v[104:107], v[8:15], v[218:225], v[104:107]


; #define PG8_STAGE(bufoff, gbase, voff) do { _Pragma("unroll") for (int _i = 0; _i < 2; ++_i) \
;         __builtin_amdgcn_global_load_lds((const unsigned*)((const char*)(gbase) + (voff)[_i]), (PG8_LAS unsigned*)(lds + (bufoff) + ldsw + _i * 8192), 16, 0, 0); } while (0)
; #define PG8_LDA(dst, b, h) do { _Pragma("unroll") for (int m = 0; m < 4; ++m) _Pragma("unroll") for (int k = 0; k < 2; ++k) dst[m][k] = *(const PG8_LAS bf16x8*)(lds + PG8_SA(b, h) + aoff + m * 2048 + k * 1024); } while (0)
; #define PG8_WAIT_V(n) asm volatile("s_waitcnt vmcnt(" #n ")" ::: "memory")
; #define PG8_WAIT_L(n) asm volatile("s_waitcnt lgkmcnt(" #n ")" ::: "memory")
; #define PG8_BAR __builtin_amdgcn_s_barrier()
; #define PG8_SCHED __builtin_amdgcn_sched_barrier(0)
; template <class Epi, class Sched, bool ALIGN_EPI = false, bool SP2 = false, bool F8 = false>
; __device__ __forceinline__ void gemm_phase(PG8_LAS unsigned char* lds, const Gemm g, const Sched& S, const Epi& E) {
;     ...
;             PG8_WAIT_V(8); PG8_WAIT_L(0); PG8_BAR; PG8_MMA(0, 0, At, B0); PG8_MMA(0, 1, At, B1); PG8_BAR; PG8_SCHED;
;             PG8_LDA(At, 1, 1); PG8_STAGE(PG8_SB(1, 0), b3, voffB); PG8_STAGE(PG8_SB(1, 1), b3 + hstep, voffB); PG8_STAGE(PG8_SA(1, 0), a3, voffA);
;             PG8_WAIT_V(8); PG8_WAIT_L(0); PG8_BAR; PG8_MMA(1, 0, At, B0); PG8_MMA(1, 1, At, B1); PG8_BAR; PG8_SCHED;
	v_mfma_f32_16x16x128_f8f6f4 v[148:151], v[16:23], v[184:191], v[148:151]
	v_mfma_f32_16x16x128_f8f6f4 v[144:147], v[24:31], v[184:191], v[144:147]
	v_mfma_f32_16x16x128_f8f6f4 v[132:135], v[16:23], v[200:207], v[132:135]
	v_mfma_f32_16x16x128_f8f6f4 v[128:131], v[24:31], v[200:207], v[128:131]
	v_mfma_f32_16x16x128_f8f6f4 v[116:119], v[16:23], v[208:215], v[116:119]
	v_mfma_f32_16x16x128_f8f6f4 v[112:115], v[24:31], v[208:215], v[112:115]
	v_mfma_f32_16x16x128_f8f6f4 v[100:103], v[16:23], v[218:225], v[100:103]
	v_mfma_f32_16x16x128_f8f6f4 v[96:99], v[24:31], v[218:225], v[96:99]
	s_setprio 0
	s_add_i32 s24, s36, s14
	s_mov_b32 m0, s24
	ds_read_b128 v[184:187], v199 offset:49152
	ds_read_b128 v[188:191], v199 offset:50176
	ds_read_b128 v[200:203], v199 offset:51200
	ds_read_b128 v[204:207], v199 offset:52224
	ds_read_b128 v[208:211], v199 offset:53248
	ds_read_b128 v[212:215], v199 offset:54272
	ds_read_b128 v[218:221], v199 offset:55296
	ds_read_b128 v[222:225], v199 offset:56320
	s_add_u32 s98, s54, 0x80
	s_addc_u32 s99, s55, 0
	global_load_lds_dwordx4 v162, s[98:99]
	s_add_i32 m0, s24, 0x2000
	s_add_u32 s24, s54, 0xb0080
	s_addc_u32 s25, s55, 0
	s_add_i32 s36, s37, s14
	s_add_u32 s100, s54, 0x80
	s_addc_u32 s101, s55, 0
	global_load_lds_dwordx4 v166, s[100:101]
	s_mov_b32 m0, s36
	s_nop 0
	global_load_lds_dwordx4 v162, s[24:25]
	s_add_i32 m0, s36, 0x2000
	s_nop 0
	global_load_lds_dwordx4 v166, s[24:25]
	s_mov_b32 m0, s33
	s_nop 0
	s_add_u32 s98, s56, 0x80
	s_addc_u32 s99, s57, 0
	global_load_lds_dwordx4 v160, s[98:99]
	s_mov_b32 m0, s43
	s_nop 0
	s_add_u32 s100, s56, 0x80
	s_addc_u32 s101, s57, 0
	global_load_lds_dwordx4 v164, s[100:101]
	s_waitcnt vmcnt(8)
	s_waitcnt lgkmcnt(0)
	s_barrier
	s_setprio 3
	s_waitcnt lgkmcnt(0)
	v_mfma_f32_16x16x128_f8f6f4 v[92:95], v[0:7], v[184:191], v[92:95]
	v_mfma_f32_16x16x128_f8f6f4 v[88:91], v[8:15], v[184:191], v[88:91]
	v_mfma_f32_16x16x128_f8f6f4 v[76:79], v[0:7], v[200:207], v[76:79]
	v_mfma_f32_16x16x128_f8f6f4 v[72:75], v[8:15], v[200:207], v[72:75]
	v_mfma_f32_16x16x128_f8f6f4 v[60:63], v[0:7], v[208:215], v[60:63]
	v_mfma_f32_16x16x128_f8f6f4 v[56:59], v[8:15], v[208:215], v[56:59]
	v_mfma_f32_16x16x128_f8f6f4 v[44:47], v[0:7], v[218:225], v[44:47]
	v_mfma_f32_16x16x128_f8f6f4 v[40:43], v[8:15], v[218:225], v[40:43]


; #define PG8_WAIT_V(n) asm volatile("s_waitcnt vmcnt(" #n ")" ::: "memory")
; #define PG8_WAIT_L(n) asm volatile("s_waitcnt lgkmcnt(" #n ")" ::: "memory")
; #define PG8_BAR __builtin_amdgcn_s_barrier()
; #define PG8_SCHED __builtin_amdgcn_sched_barrier(0)
; template <class Epi, class Sched, bool ALIGN_EPI = false, bool SP2 = false, bool F8 = false>
; __device__ __forceinline__ void gemm_phase(PG8_LAS unsigned char* lds, const Gemm g, const Sched& S, const Epi& E) {
;     ...
;         for (int t = 0; t < nt; t += 2) {
;     ...
;             PG8_WAIT_V(8); PG8_WAIT_L(0); PG8_BAR; PG8_MMA(1, 0, At, B0); PG8_MMA(1, 1, At, B1); PG8_BAR; PG8_SCHED;
	v_mfma_f32_16x16x128_f8f6f4 v[84:87], v[16:23], v[184:191], v[84:87]
	v_mfma_f32_16x16x128_f8f6f4 v[80:83], v[24:31], v[184:191], v[80:83]
	v_mfma_f32_16x16x128_f8f6f4 v[68:71], v[16:23], v[200:207], v[68:71]
	v_mfma_f32_16x16x128_f8f6f4 v[64:67], v[24:31], v[200:207], v[64:67]
	v_mfma_f32_16x16x128_f8f6f4 v[52:55], v[16:23], v[208:215], v[52:55]
	v_mfma_f32_16x16x128_f8f6f4 v[48:51], v[24:31], v[208:215], v[48:51]
	v_mfma_f32_16x16x128_f8f6f4 v[36:39], v[16:23], v[218:225], v[36:39]
	v_mfma_f32_16x16x128_f8f6f4 v[32:35], v[24:31], v[218:225], v[32:35]
	s_setprio 0
	s_add_i32 s67, s67, 2
	s_add_u32 s52, s52, 0x100
	s_addc_u32 s53, s53, 0
	s_add_u32 s65, s65, 0x100
	s_addc_u32 s66, s66, 0
	s_cmp_gt_u32 s67, 41
	s_cbranch_scc0 .Lk4_Y
